# peerq order-preserving score keys in 3 VALU (ashr, bitop3, and_or with per-column tag) instead of 5
# baseline (speedup 1.0000x reference)
.LBB0_21:
	s_and_b32 s21, s17, 0x8000
	s_waitcnt vmcnt(8)
	s_barrier
	v_add_u32_e32 v140, s21, v104
	v_or_b32_e32 v141, s21, v73
	s_add_u32 s61, s60, s21
	ds_read_b128 v[106:109], v140
	ds_read_b128 v[124:127], v141 offset:16384
	ds_read_b128 v[128:131], v141 offset:18432
	ds_read_b128 v[132:135], v141 offset:20480
	ds_read_b128 v[136:139], v141 offset:22528
	ds_read_b128 v[110:113], v140 offset:2048
	ds_read_b128 v[116:119], v140 offset:4096
	ds_read_b128 v[120:123], v140 offset:6144
	s_waitcnt lgkmcnt(6)
	v_mfma_f32_16x16x32_bf16 v[60:63], v[106:109], v[124:127], v[60:63]
	ds_read_b128 v[196:199], v140 offset:1024
	s_waitcnt lgkmcnt(6)
	v_mfma_f32_16x16x32_bf16 v[56:59], v[106:109], v[128:131], v[56:59]
	ds_read_b128 v[212:215], v141 offset:17408
	s_waitcnt lgkmcnt(6)
	v_mfma_f32_16x16x32_bf16 v[52:55], v[106:109], v[132:135], v[52:55]
	ds_read_b128 v[216:219], v141 offset:19456
	s_waitcnt lgkmcnt(6)
	v_mfma_f32_16x16x32_bf16 v[48:51], v[106:109], v[136:139], v[48:51]
	ds_read_b128 v[240:243], v141 offset:21504
	ds_read_b128 v[244:247], v141 offset:23552
	s_waitcnt lgkmcnt(7)
	v_mfma_f32_16x16x32_bf16 v[44:47], v[110:113], v[124:127], v[44:47]
	v_mfma_f32_16x16x32_bf16 v[40:43], v[110:113], v[128:131], v[40:43]
	v_mfma_f32_16x16x32_bf16 v[36:39], v[110:113], v[132:135], v[36:39]
	v_mfma_f32_16x16x32_bf16 v[32:35], v[110:113], v[136:139], v[32:35]
	ds_read_b128 v[200:203], v140 offset:3072
	ds_read_b128 v[204:207], v140 offset:5120
	s_waitcnt lgkmcnt(8)
	v_mfma_f32_16x16x32_bf16 v[28:31], v[116:119], v[124:127], v[28:31]
	v_mfma_f32_16x16x32_bf16 v[24:27], v[116:119], v[128:131], v[24:27]
	v_mfma_f32_16x16x32_bf16 v[20:23], v[116:119], v[132:135], v[20:23]
	v_mfma_f32_16x16x32_bf16 v[16:19], v[116:119], v[136:139], v[16:19]
	ds_read_b128 v[208:211], v140 offset:7168
	s_waitcnt lgkmcnt(8)
	v_mfma_f32_16x16x32_bf16 v[12:15], v[120:123], v[124:127], v[12:15]
	v_mfma_f32_16x16x32_bf16 v[8:11], v[120:123], v[128:131], v[8:11]
	v_mfma_f32_16x16x32_bf16 v[4:7], v[120:123], v[132:135], v[4:7]
	v_mfma_f32_16x16x32_bf16 v[0:3], v[120:123], v[136:139], v[0:3]
	s_waitcnt lgkmcnt(0)
	s_barrier
	s_mov_b32 m0, s61
	v_lshl_add_u64 v[106:107], v[90:91], 0, s[0:1]
	v_mfma_f32_16x16x32_bf16 v[60:63], v[196:199], v[212:215], v[60:63]
	global_load_lds_dwordx4 v[106:107], off
	v_mfma_f32_16x16x32_bf16 v[56:59], v[196:199], v[216:219], v[56:59]
	s_add_u32 m0, s61, 0x1000
	v_lshl_add_u64 v[108:109], v[88:89], 0, s[0:1]
	v_mfma_f32_16x16x32_bf16 v[52:55], v[196:199], v[240:243], v[52:55]
	global_load_lds_dwordx4 v[108:109], off
	v_mfma_f32_16x16x32_bf16 v[48:51], v[196:199], v[244:247], v[48:51]
	s_add_u32 m0, s61, 0x2000
	v_lshl_add_u64 v[110:111], v[86:87], 0, s[0:1]
	v_mfma_f32_16x16x32_bf16 v[44:47], v[200:203], v[212:215], v[44:47]
	global_load_lds_dwordx4 v[110:111], off
	v_mfma_f32_16x16x32_bf16 v[40:43], v[200:203], v[216:219], v[40:43]
	s_add_u32 m0, s61, 0x3000
	v_lshl_add_u64 v[112:113], v[84:85], 0, s[0:1]
	v_mfma_f32_16x16x32_bf16 v[36:39], v[200:203], v[240:243], v[36:39]
	global_load_lds_dwordx4 v[112:113], off
	v_mfma_f32_16x16x32_bf16 v[32:35], v[200:203], v[244:247], v[32:35]
	s_add_u32 m0, s61, 0x4000
	v_lshl_add_u64 v[116:117], v[82:83], 0, s[0:1]
	v_mfma_f32_16x16x32_bf16 v[28:31], v[204:207], v[212:215], v[28:31]
	global_load_lds_dwordx4 v[116:117], off
	v_mfma_f32_16x16x32_bf16 v[24:27], v[204:207], v[216:219], v[24:27]
	s_add_u32 m0, s61, 0x5000
	v_lshl_add_u64 v[118:119], v[78:79], 0, s[0:1]
	v_mfma_f32_16x16x32_bf16 v[20:23], v[204:207], v[240:243], v[20:23]
	global_load_lds_dwordx4 v[118:119], off
	v_mfma_f32_16x16x32_bf16 v[16:19], v[204:207], v[244:247], v[16:19]
	s_add_u32 m0, s61, 0x6000
	v_lshl_add_u64 v[120:121], v[76:77], 0, s[0:1]
	v_mfma_f32_16x16x32_bf16 v[12:15], v[208:211], v[212:215], v[12:15]
	global_load_lds_dwordx4 v[120:121], off
	v_mfma_f32_16x16x32_bf16 v[8:11], v[208:211], v[216:219], v[8:11]
	s_add_u32 m0, s61, 0x7000
	v_lshl_add_u64 v[122:123], v[74:75], 0, s[0:1]
	v_mfma_f32_16x16x32_bf16 v[4:7], v[208:211], v[240:243], v[4:7]
	global_load_lds_dwordx4 v[122:123], off
	v_mfma_f32_16x16x32_bf16 v[0:3], v[208:211], v[244:247], v[0:3]
	s_add_u32 s0, s0, 0x80
	s_addc_u32 s1, s1, 0
	s_add_i32 s17, s17, 0x8000
	s_cmpk_lg_i32 s0, 0x700
	s_cbranch_scc1 .LBB0_21
	s_waitcnt vmcnt(8)
	s_barrier
	ds_read_b128 v[74:77], v104
	ds_read_b128 v[82:85], v104 offset:2048
	ds_read_b128 v[86:89], v104 offset:4096
	ds_read_b128 v[106:109], v104 offset:6144
	ds_read_b128 v[110:113], v73 offset:16384
	ds_read_b128 v[116:119], v73 offset:18432
	ds_read_b128 v[120:123], v73 offset:20480
	ds_read_b128 v[124:127], v73 offset:22528
	s_waitcnt lgkmcnt(0)
	v_mfma_f32_16x16x32_bf16 v[60:63], v[74:77], v[110:113], v[60:63]
	v_readlane_b32 s0, v249, 30
	v_readlane_b32 s1, v249, 31
	v_readlane_b32 s22, v249, 41
	v_mfma_f32_16x16x32_bf16 v[56:59], v[74:77], v[116:119], v[56:59]
	v_readlane_b32 s23, v249, 42
	s_movk_i32 s21, 0x6f
	v_mfma_f32_16x16x32_bf16 v[52:55], v[74:77], v[120:123], v[52:55]
	v_mfma_f32_16x16x32_bf16 v[48:51], v[74:77], v[124:127], v[48:51]
	v_mfma_f32_16x16x32_bf16 v[44:47], v[82:85], v[110:113], v[44:47]
	v_mfma_f32_16x16x32_bf16 v[40:43], v[82:85], v[116:119], v[40:43]
	v_mfma_f32_16x16x32_bf16 v[36:39], v[82:85], v[120:123], v[36:39]
	v_mfma_f32_16x16x32_bf16 v[32:35], v[82:85], v[124:127], v[32:35]
	v_mfma_f32_16x16x32_bf16 v[28:31], v[86:89], v[110:113], v[28:31]
	v_mfma_f32_16x16x32_bf16 v[24:27], v[86:89], v[116:119], v[24:27]
	v_mfma_f32_16x16x32_bf16 v[20:23], v[86:89], v[120:123], v[20:23]
	v_mfma_f32_16x16x32_bf16 v[16:19], v[86:89], v[124:127], v[16:19]
	v_mfma_f32_16x16x32_bf16 v[12:15], v[106:109], v[110:113], v[12:15]
	v_mfma_f32_16x16x32_bf16 v[8:11], v[106:109], v[116:119], v[8:11]
	v_mfma_f32_16x16x32_bf16 v[4:7], v[106:109], v[120:123], v[4:7]
	v_mfma_f32_16x16x32_bf16 v[0:3], v[106:109], v[124:127], v[0:3]
	ds_read_b128 v[74:77], v104 offset:1024
	ds_read_b128 v[82:85], v104 offset:3072
	ds_read_b128 v[86:89], v104 offset:5120
	ds_read_b128 v[106:109], v104 offset:7168
	ds_read_b128 v[110:113], v73 offset:17408
	ds_read_b128 v[116:119], v73 offset:19456
	ds_read_b128 v[120:123], v73 offset:21504
	ds_read_b128 v[124:127], v73 offset:23552
	s_waitcnt lgkmcnt(0)
	s_barrier
	s_waitcnt vmcnt(0)
	s_barrier
	s_waitcnt lgkmcnt(3)
	v_mfma_f32_16x16x32_bf16 v[60:63], v[74:77], v[110:113], v[60:63]
	s_waitcnt lgkmcnt(2)
	v_mfma_f32_16x16x32_bf16 v[56:59], v[74:77], v[116:119], v[56:59]
	s_waitcnt lgkmcnt(1)
	v_mfma_f32_16x16x32_bf16 v[52:55], v[74:77], v[120:123], v[52:55]
	s_waitcnt lgkmcnt(0)
	v_mfma_f32_16x16x32_bf16 v[48:51], v[74:77], v[124:127], v[48:51]
	v_mfma_f32_16x16x32_bf16 v[44:47], v[82:85], v[110:113], v[44:47]
	v_mfma_f32_16x16x32_bf16 v[40:43], v[82:85], v[116:119], v[40:43]
	v_mfma_f32_16x16x32_bf16 v[36:39], v[82:85], v[120:123], v[36:39]
	v_mfma_f32_16x16x32_bf16 v[32:35], v[82:85], v[124:127], v[32:35]
	v_mfma_f32_16x16x32_bf16 v[28:31], v[86:89], v[110:113], v[28:31]
	v_mfma_f32_16x16x32_bf16 v[24:27], v[86:89], v[116:119], v[24:27]
	v_mfma_f32_16x16x32_bf16 v[20:23], v[86:89], v[120:123], v[20:23]
	v_mfma_f32_16x16x32_bf16 v[16:19], v[86:89], v[124:127], v[16:19]
	v_mfma_f32_16x16x32_bf16 v[12:15], v[106:109], v[110:113], v[12:15]
	v_mfma_f32_16x16x32_bf16 v[8:11], v[106:109], v[116:119], v[8:11]
	v_mfma_f32_16x16x32_bf16 v[4:7], v[106:109], v[120:123], v[4:7]
	v_mfma_f32_16x16x32_bf16 v[0:3], v[106:109], v[124:127], v[0:3]
	ds_read_b128 v[74:77], v104 offset:32768
	ds_read_b128 v[82:85], v104 offset:34816
	ds_read_b128 v[86:89], v104 offset:36864
	ds_read_b128 v[106:109], v104 offset:38912
	ds_read_b128 v[110:113], v73 offset:49152
	ds_read_b128 v[116:119], v73 offset:51200
	ds_read_b128 v[120:123], v73 offset:53248
	ds_read_b128 v[124:127], v73 offset:55296
	s_waitcnt lgkmcnt(3)
	v_mfma_f32_16x16x32_bf16 v[60:63], v[74:77], v[110:113], v[60:63]
	s_waitcnt lgkmcnt(2)
	v_mfma_f32_16x16x32_bf16 v[56:59], v[74:77], v[116:119], v[56:59]
	s_waitcnt lgkmcnt(1)
	v_mfma_f32_16x16x32_bf16 v[52:55], v[74:77], v[120:123], v[52:55]
	s_waitcnt lgkmcnt(0)
	v_mfma_f32_16x16x32_bf16 v[48:51], v[74:77], v[124:127], v[48:51]
	v_mfma_f32_16x16x32_bf16 v[44:47], v[82:85], v[110:113], v[44:47]
	v_mfma_f32_16x16x32_bf16 v[40:43], v[82:85], v[116:119], v[40:43]
	v_mfma_f32_16x16x32_bf16 v[36:39], v[82:85], v[120:123], v[36:39]
	v_mfma_f32_16x16x32_bf16 v[32:35], v[82:85], v[124:127], v[32:35]
	v_mfma_f32_16x16x32_bf16 v[28:31], v[86:89], v[110:113], v[28:31]
	v_mfma_f32_16x16x32_bf16 v[24:27], v[86:89], v[116:119], v[24:27]
	v_mfma_f32_16x16x32_bf16 v[20:23], v[86:89], v[120:123], v[20:23]
	v_mfma_f32_16x16x32_bf16 v[16:19], v[86:89], v[124:127], v[16:19]
	v_mfma_f32_16x16x32_bf16 v[12:15], v[106:109], v[110:113], v[12:15]
	v_mfma_f32_16x16x32_bf16 v[8:11], v[106:109], v[116:119], v[8:11]
	v_mfma_f32_16x16x32_bf16 v[4:7], v[106:109], v[120:123], v[4:7]
	v_mfma_f32_16x16x32_bf16 v[0:3], v[106:109], v[124:127], v[0:3]
	ds_read_b128 v[74:77], v104 offset:33792
	ds_read_b128 v[82:85], v104 offset:35840
	ds_read_b128 v[86:89], v104 offset:37888
	ds_read_b128 v[104:107], v104 offset:39936
	ds_read_b128 v[108:111], v73 offset:50176
	ds_read_b128 v[116:119], v73 offset:52224
	ds_read_b128 v[120:123], v73 offset:54272
	ds_read_b128 v[124:127], v73 offset:56320
	s_waitcnt lgkmcnt(0)
	s_barrier
	s_waitcnt lgkmcnt(0)
	s_barrier
	s_load_dwordx2 s[0:1], s[0:1], 0x130
	v_mov_b32_e32 v73, v80
	v_mfma_f32_16x16x32_bf16 v[60:63], v[74:77], v[108:111], v[60:63]
	s_waitcnt lgkmcnt(0)
	s_add_u32 s0, s0, s22
	s_addc_u32 s1, s1, s23
	s_lshl_b32 s17, s20, 15
	s_add_u32 s0, s0, s17
	s_addc_u32 s1, s1, 0
	v_mfma_f32_16x16x32_bf16 v[56:59], v[74:77], v[116:119], v[56:59]
	s_mov_b64 s[22:23], 0x80
	s_movk_i32 s17, 0x7f
	v_mfma_f32_16x16x32_bf16 v[52:55], v[74:77], v[120:123], v[52:55]
	v_mfma_f32_16x16x32_bf16 v[48:51], v[74:77], v[124:127], v[48:51]
	v_lshl_add_u64 v[74:75], s[0:1], 0, v[72:73]
	v_add_u32_e32 v73, 0x9000, v92
	v_lshl_add_u64 v[76:77], v[64:65], 1, v[74:75]
	v_readfirstlane_b32 s0, v73
	v_add_u32_e32 v73, 0xa000, v92
	s_mov_b32 m0, s0
	v_readfirstlane_b32 s0, v73
	v_add_u32_e32 v73, 0xb000, v92
	global_load_lds_dwordx4 v[76:77], off
	v_lshl_add_u64 v[78:79], v[66:67], 1, v[74:75]
	s_mov_b32 m0, s0
	v_readfirstlane_b32 s0, v73
	v_add_u32_e32 v73, 0xc000, v92
	v_mfma_f32_16x16x32_bf16 v[44:47], v[82:85], v[108:111], v[44:47]
	global_load_lds_dwordx4 v[78:79], off
	s_mov_b32 m0, s0
	v_mfma_f32_16x16x32_bf16 v[40:43], v[82:85], v[116:119], v[40:43]
	v_readfirstlane_b32 s0, v73
	v_add_u32_e32 v73, 0xd000, v92
	v_lshl_add_u64 v[76:77], v[76:77], 0, s[22:23]
	v_mfma_f32_16x16x32_bf16 v[36:39], v[82:85], v[120:123], v[36:39]
	v_mfma_f32_16x16x32_bf16 v[32:35], v[82:85], v[124:127], v[32:35]
	v_lshl_add_u64 v[82:83], v[68:69], 1, v[74:75]
	global_load_lds_dwordx4 v[82:83], off
	v_lshl_add_u64 v[74:75], v[70:71], 1, v[74:75]
	s_mov_b32 m0, s0
	v_readfirstlane_b32 s0, v73
	v_add_u32_e32 v73, 0xe000, v92
	global_load_lds_dwordx4 v[74:75], off
	s_mov_b32 m0, s0
	v_readfirstlane_b32 s0, v73
	v_add_u32_e32 v73, 0xf000, v92
	global_load_lds_dwordx4 v[76:77], off
	v_lshl_add_u64 v[76:77], v[78:79], 0, s[22:23]
	s_mov_b32 m0, s0
	v_readfirstlane_b32 s0, v73
	v_add_u32_e32 v73, 0xd000, v93
	global_load_lds_dwordx4 v[76:77], off
	v_lshl_add_u64 v[76:77], v[82:83], 0, s[22:23]
	s_mov_b32 m0, s0
	v_readfirstlane_b32 s0, v73
	global_load_lds_dwordx4 v[76:77], off
	v_lshl_add_u64 v[74:75], v[74:75], 0, s[22:23]
	s_mov_b32 m0, s0
	v_mfma_f32_16x16x32_bf16 v[28:31], v[86:89], v[108:111], v[28:31]
	global_load_lds_dwordx4 v[74:75], off
	v_lshl_or_b32 v74, s20, 9, v98
	v_mov_b32_e32 v73, v250
	v_mfma_f32_16x16x32_bf16 v[24:27], v[86:89], v[116:119], v[24:27]
	s_movk_i32 s22, 0x5f
	s_movk_i32 s23, 0x4f
	s_nop 0
	v_add_f32_e32 v60, v60, v73
	v_bfe_u32 v75, v60, 16, 1
	v_add3_u32 v75, v60, v75, s33
	v_add_u32_e32 v60, v96, v97
	v_add_f32_e32 v61, v61, v73
	ds_write_b16_d16_hi v60, v75
	v_bfe_u32 v75, v61, 16, 1
	v_add3_u32 v61, v61, v75, s33
	ds_write_b16_d16_hi v60, v61 offset:272
	v_add_f32_e32 v61, v62, v73
	v_bfe_u32 v62, v61, 16, 1
	v_add3_u32 v61, v61, v62, s33
	ds_write_b16_d16_hi v60, v61 offset:544
	v_add_f32_e32 v61, v63, v73
	v_bfe_u32 v62, v61, 16, 1
	v_add3_u32 v61, v61, v62, s33
	ds_write_b16_d16_hi v60, v61 offset:816
	v_mov_b32_e32 v61, v251
	v_add_f32_e32 v44, v44, v73
	v_add_f32_e32 v28, v28, v73
	v_mfma_f32_16x16x32_bf16 v[20:23], v[86:89], v[120:123], v[20:23]
	s_nop 0
	v_add_f32_e32 v56, v56, v61
	v_bfe_u32 v62, v56, 16, 1
	v_add3_u32 v56, v56, v62, s33
	ds_write_b16_d16_hi v60, v56 offset:32
	v_add_f32_e32 v56, v57, v61
	v_bfe_u32 v57, v56, 16, 1
	v_add3_u32 v56, v56, v57, s33
	ds_write_b16_d16_hi v60, v56 offset:304
	v_add_f32_e32 v56, v58, v61
	v_bfe_u32 v57, v56, 16, 1
	v_add3_u32 v56, v56, v57, s33
	ds_write_b16_d16_hi v60, v56 offset:576
	v_add_f32_e32 v56, v59, v61
	v_bfe_u32 v57, v56, 16, 1
	v_add3_u32 v56, v56, v57, s33
	ds_write_b16_d16_hi v60, v56 offset:848
	v_mov_b32_e32 v56, v252
	v_add_f32_e32 v40, v40, v61
	v_add_f32_e32 v24, v24, v61
	v_mfma_f32_16x16x32_bf16 v[16:19], v[86:89], v[124:127], v[16:19]
	s_nop 0
	v_add_f32_e32 v52, v52, v56
	v_bfe_u32 v57, v52, 16, 1
	v_add3_u32 v52, v52, v57, s33
	ds_write_b16_d16_hi v60, v52 offset:64
	v_add_f32_e32 v52, v53, v56
	v_bfe_u32 v53, v52, 16, 1
	v_add3_u32 v52, v52, v53, s33
	ds_write_b16_d16_hi v60, v52 offset:336
	v_add_f32_e32 v52, v54, v56
	v_bfe_u32 v53, v52, 16, 1
	v_add3_u32 v52, v52, v53, s33
	ds_write_b16_d16_hi v60, v52 offset:608
	v_add_f32_e32 v52, v55, v56
	v_bfe_u32 v53, v52, 16, 1
	v_add3_u32 v52, v52, v53, s33
	ds_write_b16_d16_hi v60, v52 offset:880
	v_mov_b32_e32 v52, v253
	v_add_f32_e32 v36, v36, v56
	v_add_f32_e32 v20, v20, v56
	v_mfma_f32_16x16x32_bf16 v[12:15], v[104:107], v[108:111], v[12:15]
	s_nop 0
	v_add_f32_e32 v48, v48, v52
	v_bfe_u32 v53, v48, 16, 1
	v_add3_u32 v48, v48, v53, s33
	ds_write_b16_d16_hi v60, v48 offset:96
	v_add_f32_e32 v48, v49, v52
	v_bfe_u32 v49, v48, 16, 1
	v_add3_u32 v48, v48, v49, s33
	ds_write_b16_d16_hi v60, v48 offset:368
	v_add_f32_e32 v48, v50, v52
	v_bfe_u32 v49, v48, 16, 1
	v_add3_u32 v48, v48, v49, s33
	ds_write_b16_d16_hi v60, v48 offset:640
	v_add_f32_e32 v48, v51, v52
	v_bfe_u32 v49, v48, 16, 1
	v_add3_u32 v48, v48, v49, s33
	ds_write_b16_d16_hi v60, v48 offset:912
	v_bfe_u32 v48, v44, 16, 1
	v_add3_u32 v44, v44, v48, s33
	ds_write_b16_d16_hi v60, v44 offset:4352
	v_add_f32_e32 v44, v45, v73
	v_bfe_u32 v45, v44, 16, 1
	v_add3_u32 v44, v44, v45, s33
	ds_write_b16_d16_hi v60, v44 offset:4624
	v_add_f32_e32 v44, v46, v73
	v_bfe_u32 v45, v44, 16, 1
	v_add3_u32 v44, v44, v45, s33
	ds_write_b16_d16_hi v100, v44 offset:272
	v_add_f32_e32 v44, v47, v73
	v_bfe_u32 v45, v44, 16, 1
	v_add3_u32 v44, v44, v45, s33
	ds_write_b16_d16_hi v100, v44 offset:544
	v_bfe_u32 v44, v40, 16, 1
	v_add3_u32 v40, v40, v44, s33
	ds_write_b16_d16_hi v60, v40 offset:4384
	v_add_f32_e32 v40, v41, v61
	v_bfe_u32 v41, v40, 16, 1
	v_add3_u32 v40, v40, v41, s33
	ds_write_b16_d16_hi v100, v40 offset:32
	v_add_f32_e32 v40, v42, v61
	v_bfe_u32 v41, v40, 16, 1
	v_add3_u32 v40, v40, v41, s33
	ds_write_b16_d16_hi v100, v40 offset:304
	v_add_f32_e32 v40, v43, v61
	v_bfe_u32 v41, v40, 16, 1
	v_add3_u32 v40, v40, v41, s33
	ds_write_b16_d16_hi v100, v40 offset:576
	v_bfe_u32 v40, v36, 16, 1
	v_add3_u32 v36, v36, v40, s33
	ds_write_b16_d16_hi v60, v36 offset:4416
	v_add_f32_e32 v36, v37, v56
	v_bfe_u32 v37, v36, 16, 1
	v_add3_u32 v36, v36, v37, s33
	ds_write_b16_d16_hi v100, v36 offset:64
	v_add_f32_e32 v36, v38, v56
	v_bfe_u32 v37, v36, 16, 1
	v_add3_u32 v36, v36, v37, s33
	ds_write_b16_d16_hi v100, v36 offset:336
	v_add_f32_e32 v36, v39, v56
	v_bfe_u32 v37, v36, 16, 1
	v_add3_u32 v36, v36, v37, s33
	v_add_f32_e32 v32, v32, v52
	ds_write_b16_d16_hi v100, v36 offset:608
	v_bfe_u32 v36, v32, 16, 1
	v_add3_u32 v32, v32, v36, s33
	ds_write_b16_d16_hi v60, v32 offset:4448
	v_add_f32_e32 v32, v33, v52
	v_bfe_u32 v33, v32, 16, 1
	v_add3_u32 v32, v32, v33, s33
	ds_write_b16_d16_hi v100, v32 offset:96
	v_add_f32_e32 v32, v34, v52
	v_bfe_u32 v33, v32, 16, 1
	v_add3_u32 v32, v32, v33, s33
	ds_write_b16_d16_hi v100, v32 offset:368
	v_add_f32_e32 v32, v35, v52
	v_bfe_u32 v33, v32, 16, 1
	v_add3_u32 v32, v32, v33, s33
	ds_write_b16_d16_hi v100, v32 offset:640
	v_bfe_u32 v32, v28, 16, 1
	v_add3_u32 v28, v28, v32, s33
	ds_write_b16_d16_hi v100, v28 offset:4080
	v_add_f32_e32 v28, v29, v73
	v_bfe_u32 v29, v28, 16, 1
	v_add3_u32 v28, v28, v29, s33
	ds_write_b16_d16_hi v100, v28 offset:4352
	v_add_f32_e32 v28, v30, v73
	v_bfe_u32 v29, v28, 16, 1
	v_add3_u32 v28, v28, v29, s33
	ds_write_b16_d16_hi v100, v28 offset:4624
	v_add_f32_e32 v28, v31, v73
	v_bfe_u32 v29, v28, 16, 1
	v_add3_u32 v28, v28, v29, s33
	ds_write_b16_d16_hi v100, v28 offset:4896
	v_bfe_u32 v28, v24, 16, 1
	v_add3_u32 v24, v24, v28, s33
	ds_write_b16_d16_hi v100, v24 offset:4112
	v_add_f32_e32 v24, v25, v61
	v_bfe_u32 v25, v24, 16, 1
	v_add3_u32 v24, v24, v25, s33
	ds_write_b16_d16_hi v100, v24 offset:4384
	v_add_f32_e32 v24, v26, v61
	v_bfe_u32 v25, v24, 16, 1
	v_add3_u32 v24, v24, v25, s33
	ds_write_b16_d16_hi v100, v24 offset:4656
	v_add_f32_e32 v24, v27, v61
	v_bfe_u32 v25, v24, 16, 1
	v_add3_u32 v24, v24, v25, s33
	ds_write_b16_d16_hi v100, v24 offset:4928
	v_bfe_u32 v24, v20, 16, 1
	v_add3_u32 v20, v20, v24, s33
	ds_write_b16_d16_hi v100, v20 offset:4144
	v_add_f32_e32 v20, v21, v56
	v_bfe_u32 v21, v20, 16, 1
	v_add3_u32 v20, v20, v21, s33
	ds_write_b16_d16_hi v100, v20 offset:4416
	v_add_f32_e32 v20, v22, v56
	v_bfe_u32 v21, v20, 16, 1
	v_add3_u32 v20, v20, v21, s33
	ds_write_b16_d16_hi v100, v20 offset:4688
	v_add_f32_e32 v20, v23, v56
	v_bfe_u32 v21, v20, 16, 1
	v_add3_u32 v20, v20, v21, s33
	v_add_f32_e32 v16, v16, v52
	ds_write_b16_d16_hi v100, v20 offset:4960
	v_bfe_u32 v20, v16, 16, 1
	v_add3_u32 v16, v16, v20, s33
	ds_write_b16_d16_hi v100, v16 offset:4176
	v_add_f32_e32 v16, v17, v52
	v_bfe_u32 v17, v16, 16, 1
	v_add3_u32 v16, v16, v17, s33
	ds_write_b16_d16_hi v100, v16 offset:4448
	v_add_f32_e32 v16, v18, v52
	v_bfe_u32 v17, v16, 16, 1
	v_add3_u32 v16, v16, v17, s33
	ds_write_b16_d16_hi v100, v16 offset:4720
	v_add_f32_e32 v16, v19, v52
	v_bfe_u32 v17, v16, 16, 1
	v_add3_u32 v16, v16, v17, s33
	v_add_f32_e32 v12, v12, v73
	ds_write_b16_d16_hi v100, v16 offset:4992
	v_bfe_u32 v16, v12, 16, 1
	v_add3_u32 v12, v12, v16, s33
	ds_write_b16_d16_hi v100, v12 offset:8432
	v_add_f32_e32 v12, v13, v73
	v_bfe_u32 v13, v12, 16, 1
	v_add3_u32 v12, v12, v13, s33
	ds_write_b16_d16_hi v100, v12 offset:8704
	v_add_f32_e32 v12, v14, v73
	v_mfma_f32_16x16x32_bf16 v[8:11], v[104:107], v[116:119], v[8:11]
	v_bfe_u32 v13, v12, 16, 1
	v_add3_u32 v12, v12, v13, s33
	ds_write_b16_d16_hi v100, v12 offset:8976
	v_add_f32_e32 v12, v15, v73
	v_bfe_u32 v13, v12, 16, 1
	v_add3_u32 v12, v12, v13, s33
	s_nop 1
	v_add_f32_e32 v8, v8, v61
	ds_write_b16_d16_hi v100, v12 offset:9248
	v_bfe_u32 v12, v8, 16, 1
	v_add3_u32 v8, v8, v12, s33
	ds_write_b16_d16_hi v100, v8 offset:8464
	v_add_f32_e32 v8, v9, v61
	v_bfe_u32 v9, v8, 16, 1
	v_add3_u32 v8, v8, v9, s33
	ds_write_b16_d16_hi v100, v8 offset:8736
	v_add_f32_e32 v8, v10, v61
	v_mfma_f32_16x16x32_bf16 v[4:7], v[104:107], v[120:123], v[4:7]
	v_bfe_u32 v9, v8, 16, 1
	v_add3_u32 v8, v8, v9, s33
	ds_write_b16_d16_hi v100, v8 offset:9008
	v_add_f32_e32 v8, v11, v61
	v_bfe_u32 v9, v8, 16, 1
	v_add3_u32 v8, v8, v9, s33
	s_nop 1
	v_add_f32_e32 v4, v4, v56
	ds_write_b16_d16_hi v100, v8 offset:9280
	v_bfe_u32 v8, v4, 16, 1
	v_add3_u32 v4, v4, v8, s33
	ds_write_b16_d16_hi v100, v4 offset:8496
	v_add_f32_e32 v4, v5, v56
	v_bfe_u32 v5, v4, 16, 1
	v_add3_u32 v4, v4, v5, s33
	ds_write_b16_d16_hi v100, v4 offset:8768
	v_add_f32_e32 v4, v6, v56
	v_mfma_f32_16x16x32_bf16 v[0:3], v[104:107], v[124:127], v[0:3]
	v_bfe_u32 v5, v4, 16, 1
	v_add3_u32 v4, v4, v5, s33
	ds_write_b16_d16_hi v100, v4 offset:9040
	v_add_f32_e32 v4, v7, v56
	v_bfe_u32 v5, v4, 16, 1
	v_add3_u32 v4, v4, v5, s33
	s_nop 1
	v_add_f32_e32 v0, v0, v52
	ds_write_b16_d16_hi v100, v4 offset:9312
	v_bfe_u32 v4, v0, 16, 1
	v_add3_u32 v0, v0, v4, s33
	ds_write_b16_d16_hi v100, v0 offset:8528
	v_add_f32_e32 v0, v1, v52
	v_bfe_u32 v1, v0, 16, 1
	v_add3_u32 v0, v0, v1, s33
	ds_write_b16_d16_hi v100, v0 offset:8800
	v_add_f32_e32 v0, v2, v52
	v_bfe_u32 v1, v0, 16, 1
	v_add3_u32 v0, v0, v1, s33
	ds_write_b16_d16_hi v100, v0 offset:9072
	v_add_f32_e32 v0, v3, v52
	v_bfe_u32 v1, v0, 16, 1
	v_add3_u32 v0, v0, v1, s33
	ds_write_b16_d16_hi v100, v0 offset:9344
	s_waitcnt vmcnt(0)
	s_waitcnt lgkmcnt(0)
	s_barrier
	ds_read_b128 v[0:3], v101
	ds_read_b128 v[4:7], v101 offset:4352
	ds_read_b128 v[8:11], v101 offset:8704
	ds_read_b128 v[12:15], v101 offset:13056
	ds_read_b128 v[16:19], v102 offset:36864
	ds_read_b128 v[20:23], v102 offset:38912
	ds_read_b128 v[24:27], v102 offset:40960
	ds_read_b128 v[28:31], v102 offset:43008
	s_waitcnt lgkmcnt(3)
	v_mfma_f32_16x16x32_bf16 v[32:35], v[0:3], v[16:19], 0
	s_waitcnt lgkmcnt(2)
	v_mfma_f32_16x16x32_bf16 v[36:39], v[0:3], v[20:23], 0
	s_waitcnt lgkmcnt(1)
	v_mfma_f32_16x16x32_bf16 v[40:43], v[0:3], v[24:27], 0
	s_waitcnt lgkmcnt(0)
	v_mfma_f32_16x16x32_bf16 v[0:3], v[0:3], v[28:31], 0
	v_mfma_f32_16x16x32_bf16 v[44:47], v[4:7], v[16:19], 0
	v_mfma_f32_16x16x32_bf16 v[48:51], v[4:7], v[20:23], 0
	v_mfma_f32_16x16x32_bf16 v[52:55], v[4:7], v[24:27], 0
	v_mfma_f32_16x16x32_bf16 v[4:7], v[4:7], v[28:31], 0
	v_mfma_f32_16x16x32_bf16 v[56:59], v[8:11], v[16:19], 0
	v_mfma_f32_16x16x32_bf16 v[60:63], v[8:11], v[20:23], 0
	v_mfma_f32_16x16x32_bf16 v[74:77], v[8:11], v[24:27], 0
	v_mfma_f32_16x16x32_bf16 v[8:11], v[8:11], v[28:31], 0
	v_mfma_f32_16x16x32_bf16 v[16:19], v[12:15], v[16:19], 0
	v_mfma_f32_16x16x32_bf16 v[20:23], v[12:15], v[20:23], 0
	v_mfma_f32_16x16x32_bf16 v[24:27], v[12:15], v[24:27], 0
	v_mfma_f32_16x16x32_bf16 v[12:15], v[12:15], v[28:31], 0
	ds_read_b128 v[28:31], v101 offset:64
	ds_read_b128 v[82:85], v101 offset:4416
	ds_read_b128 v[86:89], v101 offset:8768
	ds_read_b128 v[104:107], v101 offset:13120
	ds_read_b128 v[108:111], v102 offset:37888
	ds_read_b128 v[116:119], v102 offset:39936
	ds_read_b128 v[120:123], v102 offset:41984
	ds_read_b128 v[124:127], v102 offset:44032
	s_waitcnt lgkmcnt(3)
	v_mfma_f32_16x16x32_bf16 v[32:35], v[28:31], v[108:111], v[32:35]
	s_waitcnt lgkmcnt(2)
	v_mfma_f32_16x16x32_bf16 v[36:39], v[28:31], v[116:119], v[36:39]
	s_waitcnt lgkmcnt(1)
	v_mfma_f32_16x16x32_bf16 v[40:43], v[28:31], v[120:123], v[40:43]
	s_waitcnt lgkmcnt(0)
	v_mfma_f32_16x16x32_bf16 v[0:3], v[28:31], v[124:127], v[0:3]
	v_mfma_f32_16x16x32_bf16 v[28:31], v[82:85], v[108:111], v[44:47]
	v_mfma_f32_16x16x32_bf16 v[44:47], v[82:85], v[116:119], v[48:51]
	v_mfma_f32_16x16x32_bf16 v[48:51], v[82:85], v[120:123], v[52:55]
	v_mfma_f32_16x16x32_bf16 v[4:7], v[82:85], v[124:127], v[4:7]
	v_mfma_f32_16x16x32_bf16 v[52:55], v[86:89], v[108:111], v[56:59]
	v_mfma_f32_16x16x32_bf16 v[56:59], v[86:89], v[116:119], v[60:63]
	v_mfma_f32_16x16x32_bf16 v[60:63], v[86:89], v[120:123], v[74:77]
	v_mfma_f32_16x16x32_bf16 v[8:11], v[86:89], v[124:127], v[8:11]
	v_mfma_f32_16x16x32_bf16 v[16:19], v[104:107], v[108:111], v[16:19]
	v_mfma_f32_16x16x32_bf16 v[20:23], v[104:107], v[116:119], v[20:23]
	v_mfma_f32_16x16x32_bf16 v[24:27], v[104:107], v[120:123], v[24:27]
	v_mfma_f32_16x16x32_bf16 v[12:15], v[104:107], v[124:127], v[12:15]
	ds_read_b128 v[74:77], v101 offset:128
	ds_read_b128 v[82:85], v101 offset:4480
	ds_read_b128 v[86:89], v101 offset:8832
	ds_read_b128 v[104:107], v101 offset:13184
	ds_read_b128 v[108:111], v102 offset:53248
	ds_read_b128 v[116:119], v102 offset:55296
	ds_read_b128 v[120:123], v102 offset:57344
	ds_read_b128 v[124:127], v102 offset:59392
	s_waitcnt lgkmcnt(3)
	v_mfma_f32_16x16x32_bf16 v[32:35], v[74:77], v[108:111], v[32:35]
	s_waitcnt lgkmcnt(2)
	v_mfma_f32_16x16x32_bf16 v[36:39], v[74:77], v[116:119], v[36:39]
	s_waitcnt lgkmcnt(1)
	v_mfma_f32_16x16x32_bf16 v[40:43], v[74:77], v[120:123], v[40:43]
	s_waitcnt lgkmcnt(0)
	v_mfma_f32_16x16x32_bf16 v[0:3], v[74:77], v[124:127], v[0:3]
	v_mfma_f32_16x16x32_bf16 v[28:31], v[82:85], v[108:111], v[28:31]
	v_mfma_f32_16x16x32_bf16 v[44:47], v[82:85], v[116:119], v[44:47]
	v_mfma_f32_16x16x32_bf16 v[48:51], v[82:85], v[120:123], v[48:51]
	v_mfma_f32_16x16x32_bf16 v[4:7], v[82:85], v[124:127], v[4:7]
	v_mfma_f32_16x16x32_bf16 v[52:55], v[86:89], v[108:111], v[52:55]
	v_mfma_f32_16x16x32_bf16 v[56:59], v[86:89], v[116:119], v[56:59]
	v_mfma_f32_16x16x32_bf16 v[60:63], v[86:89], v[120:123], v[60:63]
	v_mfma_f32_16x16x32_bf16 v[8:11], v[86:89], v[124:127], v[8:11]
	v_mfma_f32_16x16x32_bf16 v[74:77], v[104:107], v[108:111], v[16:19]
	v_mfma_f32_16x16x32_bf16 v[82:85], v[104:107], v[116:119], v[20:23]
	v_mfma_f32_16x16x32_bf16 v[24:27], v[104:107], v[120:123], v[24:27]
	v_mfma_f32_16x16x32_bf16 v[86:89], v[104:107], v[124:127], v[12:15]
	s_nop 2
	ds_read_b128 v[12:15], v101 offset:192
	ds_read_b128 v[16:19], v101 offset:4544
	ds_read_b128 v[104:107], v101 offset:8896
	ds_read_b128 v[108:111], v101 offset:13248
	ds_read_b128 v[116:119], v102 offset:54272
	ds_read_b128 v[120:123], v102 offset:56320
	ds_read_b128 v[124:127], v102 offset:58368
	ds_read_b128 v[128:131], v102 offset:60416
	s_waitcnt lgkmcnt(0)
	s_barrier
	s_mov_b32 s64, 0x80000000
	s_mov_b32 s65, 0xffffff80
	v_xor_b32_e32 v250, s17, v94
	v_xor_b32_e32 v251, s21, v94
	v_xor_b32_e32 v252, s22, v94
	v_xor_b32_e32 v253, s23, v94
	v_mfma_f32_16x16x32_bf16 v[32:35], v[12:15], v[116:119], v[32:35]
	v_mfma_f32_16x16x32_bf16 v[36:39], v[12:15], v[120:123], v[36:39]
	v_mfma_f32_16x16x32_bf16 v[136:139], v[16:19], v[128:131], v[4:7]
	s_nop 5
	v_mfma_f32_16x16x32_bf16 v[4:7], v[108:111], v[124:127], v[24:27]
	s_nop 2
	v_ashrrev_i32_e32 v24, 31, v32
	v_bitop3_b32 v24, v32, v24, s64 bitop3:0x1e
	v_ashrrev_i32_e32 v26, 31, v33
	v_bitop3_b32 v26, v33, v26, s64 bitop3:0x1e
	v_ashrrev_i32_e32 v27, 31, v34
	v_bitop3_b32 v27, v34, v27, s64 bitop3:0x1e
	v_and_or_b32 v24, v24, s65, v250
	v_add_u32_e32 v25, v98, v99
	v_ashrrev_i32_e32 v32, 31, v35
	v_bitop3_b32 v32, v35, v32, s64 bitop3:0x1e
	v_and_or_b32 v26, v26, s65, v250
	v_ashrrev_i32_e32 v33, 31, v36
	v_bitop3_b32 v33, v36, v33, s64 bitop3:0x1e
	v_and_or_b32 v33, v33, s65, v251
	ds_write2_b32 v25, v24, v33 offset1:16
	v_and_or_b32 v27, v27, s65, v250
	v_ashrrev_i32_e32 v24, 31, v37
	v_bitop3_b32 v24, v37, v24, s64 bitop3:0x1e
	v_and_or_b32 v24, v24, s65, v251
	ds_write2_b32 v25, v26, v24 offset0:129 offset1:145
	v_add_u32_e32 v26, 0x400, v25
	v_mfma_f32_16x16x32_bf16 v[40:43], v[12:15], v[124:127], v[40:43]
	v_ashrrev_i32_e32 v24, 31, v38
	v_bitop3_b32 v24, v38, v24, s64 bitop3:0x1e
	v_and_or_b32 v24, v24, s65, v251
	ds_write2_b32 v26, v27, v24 offset0:2 offset1:18
	v_and_or_b32 v32, v32, s65, v250
	v_ashrrev_i32_e32 v24, 31, v39
	v_bitop3_b32 v24, v39, v24, s64 bitop3:0x1e
	v_and_or_b32 v24, v24, s65, v251
	v_mfma_f32_16x16x32_bf16 v[132:135], v[12:15], v[128:131], v[0:3]
	ds_write2_b32 v26, v32, v24 offset0:131 offset1:147
	v_ashrrev_i32_e32 v24, 31, v40
	v_bitop3_b32 v24, v40, v24, s64 bitop3:0x1e
	v_ashrrev_i32_e32 v27, 31, v41
	v_bitop3_b32 v27, v41, v27, s64 bitop3:0x1e
	v_and_or_b32 v24, v24, s65, v252
	v_ashrrev_i32_e32 v32, 31, v42
	v_bitop3_b32 v32, v42, v32, s64 bitop3:0x1e
	v_and_or_b32 v27, v27, s65, v252
	v_ashrrev_i32_e32 v33, 31, v43
	v_bitop3_b32 v33, v43, v33, s64 bitop3:0x1e
	v_and_or_b32 v32, v32, s65, v252
	v_ashrrev_i32_e32 v34, 31, v132
	v_bitop3_b32 v34, v132, v34, s64 bitop3:0x1e
	v_and_or_b32 v34, v34, s65, v253
	ds_write2_b32 v25, v24, v34 offset0:32 offset1:48
	v_mfma_f32_16x16x32_bf16 v[28:31], v[16:19], v[116:119], v[28:31]
	v_ashrrev_i32_e32 v24, 31, v133
	v_bitop3_b32 v24, v133, v24, s64 bitop3:0x1e
	v_and_or_b32 v24, v24, s65, v253
	ds_write2_b32 v25, v27, v24 offset0:161 offset1:177
	v_and_or_b32 v33, v33, s65, v252
	v_mfma_f32_16x16x32_bf16 v[44:47], v[16:19], v[120:123], v[44:47]
	v_ashrrev_i32_e32 v24, 31, v134
	v_bitop3_b32 v24, v134, v24, s64 bitop3:0x1e
	v_and_or_b32 v24, v24, s65, v253
	ds_write2_b32 v26, v32, v24 offset0:34 offset1:50
	v_mfma_f32_16x16x32_bf16 v[48:51], v[16:19], v[124:127], v[48:51]
	v_ashrrev_i32_e32 v24, 31, v135
	v_bitop3_b32 v24, v135, v24, s64 bitop3:0x1e
	v_and_or_b32 v24, v24, s65, v253
	ds_write2_b32 v26, v33, v24 offset0:163 offset1:179
	v_mfma_f32_16x16x32_bf16 v[52:55], v[104:107], v[116:119], v[52:55]
	v_ashrrev_i32_e32 v24, 31, v28
	v_bitop3_b32 v24, v28, v24, s64 bitop3:0x1e
	v_ashrrev_i32_e32 v26, 31, v29
	v_bitop3_b32 v26, v29, v26, s64 bitop3:0x1e
	v_and_or_b32 v26, v26, s65, v250
	ds_write_b32 v25, v26 offset:8772
	v_and_or_b32 v24, v24, s65, v250
	v_add_u32_e32 v25, 0x2000, v25
	v_ashrrev_i32_e32 v26, 31, v30
	v_bitop3_b32 v26, v30, v26, s64 bitop3:0x1e
	v_ashrrev_i32_e32 v27, 31, v31
	v_bitop3_b32 v27, v31, v27, s64 bitop3:0x1e
	v_ashrrev_i32_e32 v28, 31, v44
	v_bitop3_b32 v28, v44, v28, s64 bitop3:0x1e
	v_and_or_b32 v28, v28, s65, v251
	ds_write2_b32 v25, v24, v28 offset0:16 offset1:32
	v_and_or_b32 v26, v26, s65, v250
	v_ashrrev_i32_e32 v24, 31, v45
	v_bitop3_b32 v24, v45, v24, s64 bitop3:0x1e
	v_and_or_b32 v24, v24, s65, v251
	v_ashrrev_i32_e32 v28, 31, v46
	v_bitop3_b32 v28, v46, v28, s64 bitop3:0x1e
	v_and_or_b32 v28, v28, s65, v251
	v_ashrrev_i32_e32 v29, 31, v47
	v_bitop3_b32 v29, v47, v29, s64 bitop3:0x1e
	v_and_or_b32 v29, v29, s65, v251
	v_ashrrev_i32_e32 v30, 31, v48
	v_bitop3_b32 v30, v48, v30, s64 bitop3:0x1e
	v_and_or_b32 v30, v30, s65, v252
	v_ashrrev_i32_e32 v31, 31, v49
	v_bitop3_b32 v31, v49, v31, s64 bitop3:0x1e
	v_and_or_b32 v31, v31, s65, v252
	ds_write2_b32 v103, v24, v31 offset0:16 offset1:32
	v_and_or_b32 v27, v27, s65, v250
	v_ashrrev_i32_e32 v24, 31, v50
	v_bitop3_b32 v24, v50, v24, s64 bitop3:0x1e
	v_and_or_b32 v24, v24, s65, v252
	ds_write2_b32 v103, v28, v24 offset0:145 offset1:161
	v_add_u32_e32 v28, 0x400, v103
	v_mfma_f32_16x16x32_bf16 v[56:59], v[104:107], v[120:123], v[56:59]
	v_ashrrev_i32_e32 v24, 31, v51
	v_bitop3_b32 v24, v51, v24, s64 bitop3:0x1e
	v_and_or_b32 v24, v24, s65, v252
	ds_write2_b32 v28, v29, v24 offset0:18 offset1:34
	s_nop 1
	v_add_u32_e32 v29, 0x1c00, v103
	v_ashrrev_i32_e32 v24, 31, v136
	v_bitop3_b32 v24, v136, v24, s64 bitop3:0x1e
	v_and_or_b32 v24, v24, s65, v253
	ds_write2_b32 v25, v30, v24 offset0:48 offset1:64
	v_add_u32_e32 v25, 0x200, v103
	v_mfma_f32_16x16x32_bf16 v[20:23], v[104:107], v[124:127], v[60:63]
	v_ashrrev_i32_e32 v24, 31, v137
	v_bitop3_b32 v24, v137, v24, s64 bitop3:0x1e
	v_and_or_b32 v24, v24, s65, v253
	ds_write2_b32 v103, v24, v26 offset0:48 offset1:129
	v_mfma_f32_16x16x32_bf16 v[16:19], v[104:107], v[128:131], v[8:11]
	v_ashrrev_i32_e32 v24, 31, v138
	v_bitop3_b32 v24, v138, v24, s64 bitop3:0x1e
	v_and_or_b32 v24, v24, s65, v253
	ds_write2_b32 v25, v24, v27 offset0:49 offset1:130
	v_ashrrev_i32_e32 v24, 31, v139
	v_bitop3_b32 v24, v139, v24, s64 bitop3:0x1e
	v_and_or_b32 v24, v24, s65, v253
	ds_write_b32 v103, v24 offset:1224
	v_mfma_f32_16x16x32_bf16 v[12:15], v[108:111], v[116:119], v[74:77]
	s_nop 0
	v_ashrrev_i32_e32 v24, 31, v52
	v_bitop3_b32 v24, v52, v24, s64 bitop3:0x1e
	v_and_or_b32 v24, v24, s65, v250
	v_ashrrev_i32_e32 v25, 31, v53
	v_bitop3_b32 v25, v53, v25, s64 bitop3:0x1e
	v_and_or_b32 v25, v25, s65, v250
	v_ashrrev_i32_e32 v26, 31, v54
	v_bitop3_b32 v26, v54, v26, s64 bitop3:0x1e
	v_and_or_b32 v26, v26, s65, v250
	v_ashrrev_i32_e32 v27, 31, v55
	v_bitop3_b32 v27, v55, v27, s64 bitop3:0x1e
	v_and_or_b32 v27, v27, s65, v250
	v_ashrrev_i32_e32 v28, 31, v56
	v_bitop3_b32 v28, v56, v28, s64 bitop3:0x1e
	v_and_or_b32 v28, v28, s65, v251
	ds_write2_b32 v29, v24, v28 offset0:143 offset1:159
	v_add_u32_e32 v28, 0x2000, v103
	v_mfma_f32_16x16x32_bf16 v[8:11], v[108:111], v[120:123], v[82:85]
	v_ashrrev_i32_e32 v24, 31, v57
	v_bitop3_b32 v24, v57, v24, s64 bitop3:0x1e
	v_and_or_b32 v24, v24, s65, v251
	ds_write2_b32 v28, v25, v24 offset0:16 offset1:32
	v_add_u32_e32 v25, 0x2400, v103
	v_mfma_f32_16x16x32_bf16 v[0:3], v[108:111], v[128:131], v[86:89]
	v_ashrrev_i32_e32 v24, 31, v58
	v_bitop3_b32 v24, v58, v24, s64 bitop3:0x1e
	v_and_or_b32 v24, v24, s65, v251
	ds_write2_b32 v28, v26, v24 offset0:145 offset1:161
	s_nop 1
	v_ashrrev_i32_e32 v24, 31, v59
	v_bitop3_b32 v24, v59, v24, s64 bitop3:0x1e
	v_and_or_b32 v24, v24, s65, v251
	ds_write2_b32 v25, v27, v24 offset0:18 offset1:34
	s_nop 1
	v_ashrrev_i32_e32 v24, 31, v20
	v_bitop3_b32 v20, v20, v24, s64 bitop3:0x1e
	v_and_or_b32 v20, v20, s65, v252
	v_ashrrev_i32_e32 v24, 31, v21
	v_bitop3_b32 v21, v21, v24, s64 bitop3:0x1e
	v_and_or_b32 v21, v21, s65, v252
	v_ashrrev_i32_e32 v24, 31, v22
	v_bitop3_b32 v22, v22, v24, s64 bitop3:0x1e
	v_and_or_b32 v22, v22, s65, v252
	v_ashrrev_i32_e32 v24, 31, v23
	v_bitop3_b32 v23, v23, v24, s64 bitop3:0x1e
	v_and_or_b32 v23, v23, s65, v252
	v_ashrrev_i32_e32 v24, 31, v16
	v_bitop3_b32 v16, v16, v24, s64 bitop3:0x1e
	v_and_or_b32 v16, v16, s65, v253
	ds_write2_b32 v29, v20, v16 offset0:175 offset1:191
	s_nop 1
	v_ashrrev_i32_e32 v16, 31, v17
	v_bitop3_b32 v16, v17, v16, s64 bitop3:0x1e
	v_and_or_b32 v16, v16, s65, v253
	ds_write2_b32 v28, v21, v16 offset0:48 offset1:64
	s_nop 1
	v_ashrrev_i32_e32 v16, 31, v18
	v_bitop3_b32 v16, v18, v16, s64 bitop3:0x1e
	v_and_or_b32 v16, v16, s65, v253
	ds_write2_b32 v28, v22, v16 offset0:177 offset1:193
	s_nop 1
	v_ashrrev_i32_e32 v16, 31, v19
	v_bitop3_b32 v16, v19, v16, s64 bitop3:0x1e
	v_and_or_b32 v16, v16, s65, v253
	ds_write2_b32 v25, v23, v16 offset0:50 offset1:66
	s_nop 1
	v_ashrrev_i32_e32 v16, 31, v12
	v_bitop3_b32 v12, v12, v16, s64 bitop3:0x1e
	v_and_or_b32 v12, v12, s65, v250
	v_ashrrev_i32_e32 v16, 31, v13
	v_bitop3_b32 v13, v13, v16, s64 bitop3:0x1e
	v_and_or_b32 v13, v13, s65, v250
	v_ashrrev_i32_e32 v16, 31, v14
	v_bitop3_b32 v14, v14, v16, s64 bitop3:0x1e
	v_and_or_b32 v14, v14, s65, v250
	v_ashrrev_i32_e32 v16, 31, v15
	v_bitop3_b32 v15, v15, v16, s64 bitop3:0x1e
	v_and_or_b32 v15, v15, s65, v250
	v_ashrrev_i32_e32 v16, 31, v8
	v_bitop3_b32 v8, v8, v16, s64 bitop3:0x1e
	v_and_or_b32 v8, v8, s65, v251
	v_add_u32_e32 v16, 0x3c00, v103
	ds_write2_b32 v16, v12, v8 offset0:159 offset1:175
	s_nop 1
	v_ashrrev_i32_e32 v8, 31, v9
	v_bitop3_b32 v8, v9, v8, s64 bitop3:0x1e
	v_and_or_b32 v8, v8, s65, v251
	v_add_u32_e32 v9, 0x4000, v103
	ds_write2_b32 v9, v13, v8 offset0:32 offset1:48
	s_nop 1
	v_ashrrev_i32_e32 v8, 31, v10
	v_bitop3_b32 v8, v10, v8, s64 bitop3:0x1e
	v_and_or_b32 v8, v8, s65, v251
	ds_write2_b32 v9, v14, v8 offset0:161 offset1:177
	v_add_u32_e32 v10, 0x4400, v103
	s_nop 0
	v_ashrrev_i32_e32 v8, 31, v11
	v_bitop3_b32 v8, v11, v8, s64 bitop3:0x1e
	v_and_or_b32 v8, v8, s65, v251
	ds_write2_b32 v10, v15, v8 offset0:34 offset1:50
	s_nop 1
	v_ashrrev_i32_e32 v8, 31, v4
	v_bitop3_b32 v4, v4, v8, s64 bitop3:0x1e
	v_and_or_b32 v4, v4, s65, v252
	v_ashrrev_i32_e32 v8, 31, v5
	v_bitop3_b32 v5, v5, v8, s64 bitop3:0x1e
	v_and_or_b32 v5, v5, s65, v252
	v_ashrrev_i32_e32 v8, 31, v6
	v_bitop3_b32 v6, v6, v8, s64 bitop3:0x1e
	v_and_or_b32 v6, v6, s65, v252
	v_ashrrev_i32_e32 v8, 31, v7
	v_bitop3_b32 v7, v7, v8, s64 bitop3:0x1e
	v_and_or_b32 v7, v7, s65, v252
	v_ashrrev_i32_e32 v8, 31, v0
	v_bitop3_b32 v0, v0, v8, s64 bitop3:0x1e
	v_and_or_b32 v0, v0, s65, v253
	ds_write2_b32 v16, v4, v0 offset0:191 offset1:207
	s_nop 1
	v_ashrrev_i32_e32 v0, 31, v1
	v_bitop3_b32 v0, v1, v0, s64 bitop3:0x1e
	v_and_or_b32 v0, v0, s65, v253
	ds_write2_b32 v9, v5, v0 offset0:64 offset1:80
	s_nop 1
	v_ashrrev_i32_e32 v0, 31, v2
	v_bitop3_b32 v0, v2, v0, s64 bitop3:0x1e
	v_and_or_b32 v0, v0, s65, v253
	ds_write2_b32 v9, v6, v0 offset0:193 offset1:209
	s_nop 1
	v_ashrrev_i32_e32 v0, 31, v3
	v_bitop3_b32 v0, v3, v0, s64 bitop3:0x1e
	v_and_or_b32 v0, v0, s65, v253
	ds_write2_b32 v10, v7, v0 offset0:66 offset1:82
	s_waitcnt lgkmcnt(0)
	s_barrier
	s_mov_b64 s[0:1], exec
	v_lshrrev_b32_e32 v116, 1, v81
	v_and_b32_e32 v117, 1, v81
	v_readlane_b32 s22, v249, 30
	v_readlane_b32 s23, v249, 31
	v_mul_u32_u24_e32 v118, 0x204, v116
	v_lshl_add_u32 v118, v117, 8, v118
	s_load_dwordx2 s[22:23], s[22:23], 0x180
	ds_read2_b32 v[0:1], v118 offset0:0 offset1:1
	ds_read2_b32 v[2:3], v118 offset0:2 offset1:3
	ds_read2_b32 v[4:5], v118 offset0:4 offset1:5
	ds_read2_b32 v[6:7], v118 offset0:6 offset1:7
	ds_read2_b32 v[8:9], v118 offset0:8 offset1:9
	ds_read2_b32 v[10:11], v118 offset0:10 offset1:11
	ds_read2_b32 v[12:13], v118 offset0:12 offset1:13
	ds_read2_b32 v[14:15], v118 offset0:14 offset1:15
	ds_read2_b32 v[16:17], v118 offset0:16 offset1:17
	ds_read2_b32 v[18:19], v118 offset0:18 offset1:19
	ds_read2_b32 v[20:21], v118 offset0:20 offset1:21
	ds_read2_b32 v[22:23], v118 offset0:22 offset1:23
	ds_read2_b32 v[24:25], v118 offset0:24 offset1:25
	ds_read2_b32 v[26:27], v118 offset0:26 offset1:27
	ds_read2_b32 v[28:29], v118 offset0:28 offset1:29
	ds_read2_b32 v[30:31], v118 offset0:30 offset1:31
	ds_read2_b32 v[32:33], v118 offset0:32 offset1:33
	ds_read2_b32 v[34:35], v118 offset0:34 offset1:35
	ds_read2_b32 v[36:37], v118 offset0:36 offset1:37
	ds_read2_b32 v[38:39], v118 offset0:38 offset1:39
	ds_read2_b32 v[40:41], v118 offset0:40 offset1:41
	ds_read2_b32 v[42:43], v118 offset0:42 offset1:43
	ds_read2_b32 v[44:45], v118 offset0:44 offset1:45
	ds_read2_b32 v[46:47], v118 offset0:46 offset1:47
	ds_read2_b32 v[48:49], v118 offset0:48 offset1:49
	ds_read2_b32 v[50:51], v118 offset0:50 offset1:51
	ds_read2_b32 v[52:53], v118 offset0:52 offset1:53
	ds_read2_b32 v[54:55], v118 offset0:54 offset1:55
	ds_read2_b32 v[56:57], v118 offset0:56 offset1:57
	ds_read2_b32 v[58:59], v118 offset0:58 offset1:59
	ds_read2_b32 v[60:61], v118 offset0:60 offset1:61
	ds_read2_b32 v[62:63], v118 offset0:62 offset1:63
	s_waitcnt lgkmcnt(0)
	v_max_u32_e32 v104, v0, v1
	v_min_u32_e32 v1, v0, v1
	v_max_u32_e32 v105, v16, v17
	v_min_u32_e32 v17, v16, v17
	v_max_u32_e32 v106, v32, v33
	v_min_u32_e32 v33, v32, v33
	v_max_u32_e32 v107, v48, v49
	v_min_u32_e32 v49, v48, v49
	v_max_u32_e32 v108, v2, v3
	v_min_u32_e32 v3, v2, v3
	v_max_u32_e32 v109, v18, v19
	v_min_u32_e32 v19, v18, v19
	v_max_u32_e32 v110, v34, v35
	v_min_u32_e32 v35, v34, v35
	v_max_u32_e32 v111, v50, v51
	v_min_u32_e32 v51, v50, v51
	v_max_u32_e32 v0, v104, v108
	v_min_u32_e32 v108, v104, v108
	v_max_u32_e32 v16, v105, v109
	v_min_u32_e32 v109, v105, v109
	v_max_u32_e32 v32, v106, v110
	v_min_u32_e32 v110, v106, v110
	v_max_u32_e32 v48, v107, v111
	v_min_u32_e32 v111, v107, v111
	v_max_u32_e32 v2, v1, v3
	v_min_u32_e32 v3, v1, v3
	v_max_u32_e32 v18, v17, v19
	v_min_u32_e32 v19, v17, v19
	v_max_u32_e32 v34, v33, v35
	v_min_u32_e32 v35, v33, v35
	v_max_u32_e32 v50, v49, v51
	v_min_u32_e32 v51, v49, v51
	v_max_u32_e32 v104, v2, v108
	v_min_u32_e32 v108, v2, v108
	v_max_u32_e32 v105, v18, v109
	v_min_u32_e32 v109, v18, v109
	v_max_u32_e32 v106, v34, v110
	v_min_u32_e32 v110, v34, v110
	v_max_u32_e32 v107, v50, v111
	v_min_u32_e32 v111, v50, v111
	v_max_u32_e32 v1, v4, v5
	v_min_u32_e32 v5, v4, v5
	v_max_u32_e32 v17, v20, v21
	v_min_u32_e32 v21, v20, v21
	v_max_u32_e32 v33, v36, v37
	v_min_u32_e32 v37, v36, v37
	v_max_u32_e32 v49, v52, v53
	v_min_u32_e32 v53, v52, v53
	v_max_u32_e32 v2, v6, v7
	v_min_u32_e32 v7, v6, v7
	v_max_u32_e32 v18, v22, v23
	v_min_u32_e32 v23, v22, v23
	v_max_u32_e32 v34, v38, v39
	v_min_u32_e32 v39, v38, v39
	v_max_u32_e32 v50, v54, v55
	v_min_u32_e32 v55, v54, v55
	v_max_u32_e32 v4, v1, v2
	v_min_u32_e32 v2, v1, v2
	v_max_u32_e32 v20, v17, v18
	v_min_u32_e32 v18, v17, v18
	v_max_u32_e32 v36, v33, v34
	v_min_u32_e32 v34, v33, v34
	v_max_u32_e32 v52, v49, v50
	v_min_u32_e32 v50, v49, v50
	v_max_u32_e32 v6, v5, v7
	v_min_u32_e32 v7, v5, v7
	v_max_u32_e32 v22, v21, v23
	v_min_u32_e32 v23, v21, v23
	v_max_u32_e32 v38, v37, v39
	v_min_u32_e32 v39, v37, v39
	v_max_u32_e32 v54, v53, v55
	v_min_u32_e32 v55, v53, v55
	v_max_u32_e32 v1, v6, v2
	v_min_u32_e32 v2, v6, v2
	v_max_u32_e32 v17, v22, v18
	v_min_u32_e32 v18, v22, v18
	v_max_u32_e32 v33, v38, v34
	v_min_u32_e32 v34, v38, v34
	v_max_u32_e32 v49, v54, v50
	v_min_u32_e32 v50, v54, v50
	v_max_u32_e32 v5, v0, v4
	v_min_u32_e32 v4, v0, v4
	v_max_u32_e32 v21, v16, v20
	v_min_u32_e32 v20, v16, v20
	v_max_u32_e32 v37, v32, v36
	v_min_u32_e32 v36, v32, v36
	v_max_u32_e32 v53, v48, v52
	v_min_u32_e32 v52, v48, v52
	v_max_u32_e32 v6, v108, v2
	v_min_u32_e32 v2, v108, v2
	v_max_u32_e32 v22, v109, v18
	v_min_u32_e32 v18, v109, v18
	v_max_u32_e32 v38, v110, v34
	v_min_u32_e32 v34, v110, v34
	v_max_u32_e32 v54, v111, v50
	v_min_u32_e32 v50, v111, v50
	v_max_u32_e32 v0, v6, v4
	v_min_u32_e32 v4, v6, v4
	v_max_u32_e32 v16, v22, v20
	v_min_u32_e32 v20, v22, v20
	v_max_u32_e32 v32, v38, v36
	v_min_u32_e32 v36, v38, v36
	v_max_u32_e32 v48, v54, v52
	v_min_u32_e32 v52, v54, v52
	v_max_u32_e32 v108, v104, v1
	v_min_u32_e32 v1, v104, v1
	v_max_u32_e32 v109, v105, v17
	v_min_u32_e32 v17, v105, v17
	v_max_u32_e32 v110, v106, v33
	v_min_u32_e32 v33, v106, v33
	v_max_u32_e32 v111, v107, v49
	v_min_u32_e32 v49, v107, v49
	v_max_u32_e32 v6, v3, v7
	v_min_u32_e32 v7, v3, v7
	v_max_u32_e32 v22, v19, v23
	v_min_u32_e32 v23, v19, v23
	v_max_u32_e32 v38, v35, v39
	v_min_u32_e32 v39, v35, v39
	v_max_u32_e32 v54, v51, v55
	v_min_u32_e32 v55, v51, v55
	v_max_u32_e32 v104, v6, v1
	v_min_u32_e32 v1, v6, v1
	v_max_u32_e32 v105, v22, v17
	v_min_u32_e32 v17, v22, v17
	v_max_u32_e32 v106, v38, v33
	v_min_u32_e32 v33, v38, v33
	v_max_u32_e32 v107, v54, v49
	v_min_u32_e32 v49, v54, v49
	v_max_u32_e32 v3, v108, v0
	v_min_u32_e32 v0, v108, v0
	v_max_u32_e32 v19, v109, v16
	v_min_u32_e32 v16, v109, v16
	v_max_u32_e32 v35, v110, v32
	v_min_u32_e32 v32, v110, v32
	v_max_u32_e32 v51, v111, v48
	v_min_u32_e32 v48, v111, v48
	v_max_u32_e32 v6, v104, v4
	v_min_u32_e32 v4, v104, v4
	v_max_u32_e32 v22, v105, v20
	v_min_u32_e32 v20, v105, v20
	v_max_u32_e32 v38, v106, v36
	v_min_u32_e32 v36, v106, v36
	v_max_u32_e32 v54, v107, v52
	v_min_u32_e32 v52, v107, v52
	v_max_u32_e32 v108, v1, v2
	v_min_u32_e32 v2, v1, v2
	v_max_u32_e32 v109, v17, v18
	v_min_u32_e32 v18, v17, v18
	v_max_u32_e32 v110, v33, v34
	v_min_u32_e32 v34, v33, v34
	v_max_u32_e32 v111, v49, v50
	v_min_u32_e32 v50, v49, v50
	v_max_u32_e32 v104, v8, v9
	v_min_u32_e32 v9, v8, v9
	v_max_u32_e32 v105, v24, v25
	v_min_u32_e32 v25, v24, v25
	v_max_u32_e32 v106, v40, v41
	v_min_u32_e32 v41, v40, v41
	v_max_u32_e32 v107, v56, v57
	v_min_u32_e32 v57, v56, v57
	v_max_u32_e32 v1, v10, v11
	v_min_u32_e32 v11, v10, v11
	v_max_u32_e32 v17, v26, v27
	v_min_u32_e32 v27, v26, v27
	v_max_u32_e32 v33, v42, v43
	v_min_u32_e32 v43, v42, v43
	v_max_u32_e32 v49, v58, v59
	v_min_u32_e32 v59, v58, v59
	v_max_u32_e32 v8, v104, v1
	v_min_u32_e32 v1, v104, v1
	v_max_u32_e32 v24, v105, v17
	v_min_u32_e32 v17, v105, v17
	v_max_u32_e32 v40, v106, v33
	v_min_u32_e32 v33, v106, v33
	v_max_u32_e32 v56, v107, v49
	v_min_u32_e32 v49, v107, v49
	v_max_u32_e32 v10, v9, v11
	v_min_u32_e32 v11, v9, v11
	v_max_u32_e32 v26, v25, v27
	v_min_u32_e32 v27, v25, v27
	v_max_u32_e32 v42, v41, v43
	v_min_u32_e32 v43, v41, v43
	v_max_u32_e32 v58, v57, v59
	v_min_u32_e32 v59, v57, v59
	v_max_u32_e32 v104, v10, v1
	v_min_u32_e32 v1, v10, v1
	v_max_u32_e32 v105, v26, v17
	v_min_u32_e32 v17, v26, v17
	v_max_u32_e32 v106, v42, v33
	v_min_u32_e32 v33, v42, v33
	v_max_u32_e32 v107, v58, v49
	v_min_u32_e32 v49, v58, v49
	v_max_u32_e32 v9, v12, v13
	v_min_u32_e32 v13, v12, v13
	v_max_u32_e32 v25, v28, v29
	v_min_u32_e32 v29, v28, v29
	v_max_u32_e32 v41, v44, v45
	v_min_u32_e32 v45, v44, v45
	v_max_u32_e32 v57, v60, v61
	v_min_u32_e32 v61, v60, v61
	v_max_u32_e32 v10, v14, v15
	v_min_u32_e32 v15, v14, v15
	v_max_u32_e32 v26, v30, v31
	v_min_u32_e32 v31, v30, v31
	v_max_u32_e32 v42, v46, v47
	v_min_u32_e32 v47, v46, v47
	v_max_u32_e32 v58, v62, v63
	v_min_u32_e32 v63, v62, v63
	v_max_u32_e32 v12, v9, v10
	v_min_u32_e32 v10, v9, v10
	v_max_u32_e32 v28, v25, v26
	v_min_u32_e32 v26, v25, v26
	v_max_u32_e32 v44, v41, v42
	v_min_u32_e32 v42, v41, v42
	v_max_u32_e32 v60, v57, v58
	v_min_u32_e32 v58, v57, v58
	v_max_u32_e32 v14, v13, v15
	v_min_u32_e32 v15, v13, v15
	v_max_u32_e32 v30, v29, v31
	v_min_u32_e32 v31, v29, v31
	v_max_u32_e32 v46, v45, v47
	v_min_u32_e32 v47, v45, v47
	v_max_u32_e32 v62, v61, v63
	v_min_u32_e32 v63, v61, v63
	v_max_u32_e32 v9, v14, v10
	v_min_u32_e32 v10, v14, v10
	v_max_u32_e32 v25, v30, v26
	v_min_u32_e32 v26, v30, v26
	v_max_u32_e32 v41, v46, v42
	v_min_u32_e32 v42, v46, v42
	v_max_u32_e32 v57, v62, v58
	v_min_u32_e32 v58, v62, v58
	v_max_u32_e32 v13, v8, v12
	v_min_u32_e32 v12, v8, v12
	v_max_u32_e32 v29, v24, v28
	v_min_u32_e32 v28, v24, v28
	v_max_u32_e32 v45, v40, v44
	v_min_u32_e32 v44, v40, v44
	v_max_u32_e32 v61, v56, v60
	v_min_u32_e32 v60, v56, v60
	v_max_u32_e32 v14, v1, v10
	v_min_u32_e32 v10, v1, v10
	v_max_u32_e32 v30, v17, v26
	v_min_u32_e32 v26, v17, v26
	v_max_u32_e32 v46, v33, v42
	v_min_u32_e32 v42, v33, v42
	v_max_u32_e32 v62, v49, v58
	v_min_u32_e32 v58, v49, v58
	v_max_u32_e32 v8, v14, v12
	v_min_u32_e32 v12, v14, v12
	v_max_u32_e32 v24, v30, v28
	v_min_u32_e32 v28, v30, v28
	v_max_u32_e32 v40, v46, v44
	v_min_u32_e32 v44, v46, v44
	v_max_u32_e32 v56, v62, v60
	v_min_u32_e32 v60, v62, v60
	v_max_u32_e32 v1, v104, v9
	v_min_u32_e32 v9, v104, v9
	v_max_u32_e32 v17, v105, v25
	v_min_u32_e32 v25, v105, v25
	v_max_u32_e32 v33, v106, v41
	v_min_u32_e32 v41, v106, v41
	v_max_u32_e32 v49, v107, v57
	v_min_u32_e32 v57, v107, v57
	v_max_u32_e32 v14, v11, v15
	v_min_u32_e32 v15, v11, v15
	v_max_u32_e32 v30, v27, v31
	v_min_u32_e32 v31, v27, v31
	v_max_u32_e32 v46, v43, v47
	v_min_u32_e32 v47, v43, v47
	v_max_u32_e32 v62, v59, v63
	v_min_u32_e32 v63, v59, v63
	v_max_u32_e32 v104, v14, v9
	v_min_u32_e32 v9, v14, v9
	v_max_u32_e32 v105, v30, v25
	v_min_u32_e32 v25, v30, v25
	v_max_u32_e32 v106, v46, v41
	v_min_u32_e32 v41, v46, v41
	v_max_u32_e32 v107, v62, v57
	v_min_u32_e32 v57, v62, v57
	v_max_u32_e32 v11, v1, v8
	v_min_u32_e32 v8, v1, v8
	v_max_u32_e32 v27, v17, v24
	v_min_u32_e32 v24, v17, v24
	v_max_u32_e32 v43, v33, v40
	v_min_u32_e32 v40, v33, v40
	v_max_u32_e32 v59, v49, v56
	v_min_u32_e32 v56, v49, v56
	v_max_u32_e32 v14, v104, v12
	v_min_u32_e32 v12, v104, v12
	v_max_u32_e32 v30, v105, v28
	v_min_u32_e32 v28, v105, v28
	v_max_u32_e32 v46, v106, v44
	v_min_u32_e32 v44, v106, v44
	v_max_u32_e32 v62, v107, v60
	v_min_u32_e32 v60, v107, v60
	v_max_u32_e32 v1, v9, v10
	v_min_u32_e32 v10, v9, v10
	v_max_u32_e32 v17, v25, v26
	v_min_u32_e32 v26, v25, v26
	v_max_u32_e32 v33, v41, v42
	v_min_u32_e32 v42, v41, v42
	v_max_u32_e32 v49, v57, v58
	v_min_u32_e32 v58, v57, v58
	v_max_u32_e32 v104, v5, v13
	v_min_u32_e32 v13, v5, v13
	v_max_u32_e32 v105, v21, v29
	v_min_u32_e32 v29, v21, v29
	v_max_u32_e32 v106, v37, v45
	v_min_u32_e32 v45, v37, v45
	v_max_u32_e32 v107, v53, v61
	v_min_u32_e32 v61, v53, v61
	v_max_u32_e32 v9, v4, v12
	v_min_u32_e32 v12, v4, v12
	v_max_u32_e32 v25, v20, v28
	v_min_u32_e32 v28, v20, v28
	v_max_u32_e32 v41, v36, v44
	v_min_u32_e32 v44, v36, v44
	v_max_u32_e32 v57, v52, v60
	v_min_u32_e32 v60, v52, v60
	v_max_u32_e32 v5, v9, v13
	v_min_u32_e32 v13, v9, v13
	v_max_u32_e32 v21, v25, v29
	v_min_u32_e32 v29, v25, v29
	v_max_u32_e32 v37, v41, v45
	v_min_u32_e32 v45, v41, v45
	v_max_u32_e32 v53, v57, v61
	v_min_u32_e32 v61, v57, v61
	v_max_u32_e32 v4, v0, v8
	v_min_u32_e32 v8, v0, v8
	v_max_u32_e32 v20, v16, v24
	v_min_u32_e32 v24, v16, v24
	v_max_u32_e32 v36, v32, v40
	v_min_u32_e32 v40, v32, v40
	v_max_u32_e32 v52, v48, v56
	v_min_u32_e32 v56, v48, v56
	v_max_u32_e32 v9, v2, v10
	v_min_u32_e32 v10, v2, v10
	v_max_u32_e32 v25, v18, v26
	v_min_u32_e32 v26, v18, v26
	v_max_u32_e32 v41, v34, v42
	v_min_u32_e32 v42, v34, v42
	v_max_u32_e32 v57, v50, v58
	v_min_u32_e32 v58, v50, v58
	v_max_u32_e32 v0, v9, v8
	v_min_u32_e32 v8, v9, v8
	v_max_u32_e32 v16, v25, v24
	v_min_u32_e32 v24, v25, v24
	v_max_u32_e32 v32, v41, v40
	v_min_u32_e32 v40, v41, v40
	v_max_u32_e32 v48, v57, v56
	v_min_u32_e32 v56, v57, v56
	v_max_u32_e32 v2, v4, v5
	v_min_u32_e32 v5, v4, v5
	v_max_u32_e32 v18, v20, v21
	v_min_u32_e32 v21, v20, v21
	v_max_u32_e32 v34, v36, v37
	v_min_u32_e32 v37, v36, v37
	v_max_u32_e32 v50, v52, v53
	v_min_u32_e32 v53, v52, v53
	v_max_u32_e32 v9, v0, v13
	v_min_u32_e32 v13, v0, v13
	v_max_u32_e32 v25, v16, v29
	v_min_u32_e32 v29, v16, v29
	v_max_u32_e32 v41, v32, v45
	v_min_u32_e32 v45, v32, v45
	v_max_u32_e32 v57, v48, v61
	v_min_u32_e32 v61, v48, v61
	v_max_u32_e32 v4, v8, v12
	v_min_u32_e32 v12, v8, v12
	v_max_u32_e32 v20, v24, v28
	v_min_u32_e32 v28, v24, v28
	v_max_u32_e32 v36, v40, v44
	v_min_u32_e32 v44, v40, v44
	v_max_u32_e32 v52, v56, v60
	v_min_u32_e32 v60, v56, v60
	v_max_u32_e32 v0, v3, v11
	v_min_u32_e32 v11, v3, v11
	v_max_u32_e32 v16, v19, v27
	v_min_u32_e32 v27, v19, v27
	v_max_u32_e32 v32, v35, v43
	v_min_u32_e32 v43, v35, v43
	v_max_u32_e32 v48, v51, v59
	v_min_u32_e32 v59, v51, v59
	v_max_u32_e32 v8, v108, v1
	v_min_u32_e32 v1, v108, v1
	v_max_u32_e32 v24, v109, v17
	v_min_u32_e32 v17, v109, v17
	v_max_u32_e32 v40, v110, v33
	v_min_u32_e32 v33, v110, v33
	v_max_u32_e32 v56, v111, v49
	v_min_u32_e32 v49, v111, v49
	v_max_u32_e32 v3, v8, v11
	v_min_u32_e32 v11, v8, v11
	v_max_u32_e32 v19, v24, v27
	v_min_u32_e32 v27, v24, v27
	v_max_u32_e32 v35, v40, v43
	v_min_u32_e32 v43, v40, v43
	v_max_u32_e32 v51, v56, v59
	v_min_u32_e32 v59, v56, v59
	v_max_u32_e32 v108, v6, v14
	v_min_u32_e32 v14, v6, v14
	v_max_u32_e32 v109, v22, v30
	v_min_u32_e32 v30, v22, v30
	v_max_u32_e32 v110, v38, v46
	v_min_u32_e32 v46, v38, v46
	v_max_u32_e32 v111, v54, v62
	v_min_u32_e32 v62, v54, v62
	v_max_u32_e32 v8, v7, v15
	v_min_u32_e32 v15, v7, v15
	v_max_u32_e32 v24, v23, v31
	v_min_u32_e32 v31, v23, v31
	v_max_u32_e32 v40, v39, v47
	v_min_u32_e32 v47, v39, v47
	v_max_u32_e32 v56, v55, v63
	v_min_u32_e32 v63, v55, v63
	v_max_u32_e32 v6, v8, v14
	v_min_u32_e32 v14, v8, v14
	v_max_u32_e32 v22, v24, v30
	v_min_u32_e32 v30, v24, v30
	v_max_u32_e32 v38, v40, v46
	v_min_u32_e32 v46, v40, v46
	v_max_u32_e32 v54, v56, v62
	v_min_u32_e32 v62, v56, v62
	v_max_u32_e32 v7, v108, v3
	v_min_u32_e32 v3, v108, v3
	v_max_u32_e32 v23, v109, v19
	v_min_u32_e32 v19, v109, v19
	v_max_u32_e32 v39, v110, v35
	v_min_u32_e32 v35, v110, v35
	v_max_u32_e32 v55, v111, v51
	v_min_u32_e32 v51, v111, v51
	v_max_u32_e32 v8, v6, v11
	v_min_u32_e32 v11, v6, v11
	v_max_u32_e32 v24, v22, v27
	v_min_u32_e32 v27, v22, v27
	v_max_u32_e32 v40, v38, v43
	v_min_u32_e32 v43, v38, v43
	v_max_u32_e32 v56, v54, v59
	v_min_u32_e32 v59, v54, v59
	v_max_u32_e32 v108, v14, v1
	v_min_u32_e32 v1, v14, v1
	v_max_u32_e32 v109, v30, v17
	v_min_u32_e32 v17, v30, v17
	v_max_u32_e32 v110, v46, v33
	v_min_u32_e32 v33, v46, v33
	v_max_u32_e32 v111, v62, v49
	v_min_u32_e32 v49, v62, v49
	v_max_u32_e32 v6, v0, v2
	v_min_u32_e32 v2, v0, v2
	v_max_u32_e32 v22, v16, v18
	v_min_u32_e32 v18, v16, v18
	v_max_u32_e32 v38, v32, v34
	v_min_u32_e32 v34, v32, v34
	v_max_u32_e32 v54, v48, v50
	v_min_u32_e32 v50, v48, v50
	v_max_u32_e32 v14, v7, v5
	v_min_u32_e32 v5, v7, v5
	v_max_u32_e32 v30, v23, v21
	v_min_u32_e32 v21, v23, v21
	v_max_u32_e32 v46, v39, v37
	v_min_u32_e32 v37, v39, v37
	v_max_u32_e32 v62, v55, v53
	v_min_u32_e32 v53, v55, v53
	v_max_u32_e32 v0, v3, v9
	v_min_u32_e32 v9, v3, v9
	v_max_u32_e32 v16, v19, v25
	v_min_u32_e32 v25, v19, v25
	v_max_u32_e32 v32, v35, v41
	v_min_u32_e32 v41, v35, v41
	v_max_u32_e32 v48, v51, v57
	v_min_u32_e32 v57, v51, v57
	v_max_u32_e32 v7, v8, v13
	v_min_u32_e32 v13, v8, v13
	v_max_u32_e32 v23, v24, v29
	v_min_u32_e32 v29, v24, v29
	v_max_u32_e32 v39, v40, v45
	v_min_u32_e32 v45, v40, v45
	v_max_u32_e32 v55, v56, v61
	v_min_u32_e32 v61, v56, v61
	v_max_u32_e32 v3, v11, v4
	v_min_u32_e32 v4, v11, v4
	v_max_u32_e32 v19, v27, v20
	v_min_u32_e32 v20, v27, v20
	v_max_u32_e32 v35, v43, v36
	v_min_u32_e32 v36, v43, v36
	v_max_u32_e32 v51, v59, v52
	v_min_u32_e32 v52, v59, v52
	v_max_u32_e32 v8, v108, v12
	v_min_u32_e32 v12, v108, v12
	v_max_u32_e32 v24, v109, v28
	v_min_u32_e32 v28, v109, v28
	v_max_u32_e32 v40, v110, v44
	v_min_u32_e32 v44, v110, v44
	v_max_u32_e32 v56, v111, v60
	v_min_u32_e32 v60, v111, v60
	v_max_u32_e32 v11, v1, v10
	v_min_u32_e32 v10, v1, v10
	v_max_u32_e32 v27, v17, v26
	v_min_u32_e32 v26, v17, v26
	v_max_u32_e32 v43, v33, v42
	v_min_u32_e32 v42, v33, v42
	v_max_u32_e32 v59, v49, v58
	v_min_u32_e32 v58, v49, v58
	v_max_u32_e32 v108, v104, v31
	v_max_u32_e32 v109, v6, v26
	v_max_u32_e32 v110, v2, v27
	v_max_u32_e32 v111, v14, v28
	v_max_u32_e32 v1, v5, v24
	v_max_u32_e32 v17, v0, v20
	v_max_u32_e32 v33, v9, v19
	v_max_u32_e32 v49, v7, v29
	v_max_u32_e32 v104, v13, v23
	v_max_u32_e32 v31, v3, v25
	v_max_u32_e32 v6, v4, v16
	v_max_u32_e32 v26, v8, v21
	v_max_u32_e32 v2, v12, v30
	v_max_u32_e32 v27, v11, v18
	v_max_u32_e32 v14, v10, v22
	v_max_u32_e32 v28, v15, v105
	v_max_u32_e32 v5, v108, v104
	v_min_u32_e32 v104, v108, v104
	v_max_u32_e32 v24, v109, v31
	v_min_u32_e32 v31, v109, v31
	v_max_u32_e32 v0, v110, v6
	v_min_u32_e32 v6, v110, v6
	v_max_u32_e32 v20, v111, v26
	v_min_u32_e32 v26, v111, v26
	v_max_u32_e32 v9, v1, v2
	v_min_u32_e32 v2, v1, v2
	v_max_u32_e32 v19, v17, v27
	v_min_u32_e32 v27, v17, v27
	v_max_u32_e32 v7, v33, v14
	v_min_u32_e32 v14, v33, v14
	v_max_u32_e32 v29, v49, v28
	v_min_u32_e32 v28, v49, v28
	v_max_u32_e32 v13, v5, v9
	v_min_u32_e32 v9, v5, v9
	v_max_u32_e32 v23, v24, v19
	v_min_u32_e32 v19, v24, v19
	v_max_u32_e32 v3, v0, v7
	v_min_u32_e32 v7, v0, v7
	v_max_u32_e32 v25, v20, v29
	v_min_u32_e32 v29, v20, v29
	v_max_u32_e32 v4, v104, v2
	v_min_u32_e32 v2, v104, v2
	v_max_u32_e32 v16, v31, v27
	v_min_u32_e32 v27, v31, v27
	v_max_u32_e32 v8, v6, v14
	v_min_u32_e32 v14, v6, v14
	v_max_u32_e32 v21, v26, v28
	v_min_u32_e32 v28, v26, v28
	v_max_u32_e32 v12, v13, v3
	v_min_u32_e32 v3, v13, v3
	v_max_u32_e32 v30, v23, v25
	v_min_u32_e32 v25, v23, v25
	v_max_u32_e32 v11, v9, v7
	v_min_u32_e32 v7, v9, v7
	v_max_u32_e32 v18, v19, v29
	v_min_u32_e32 v29, v19, v29
	v_max_u32_e32 v10, v4, v8
	v_min_u32_e32 v8, v4, v8
	v_max_u32_e32 v22, v16, v21
	v_min_u32_e32 v21, v16, v21
	v_max_u32_e32 v15, v2, v14
	v_min_u32_e32 v14, v2, v14
	v_max_u32_e32 v105, v27, v28
	v_min_u32_e32 v28, v27, v28
	v_max_u32_e32 v108, v12, v30
	v_min_u32_e32 v30, v12, v30
	v_max_u32_e32 v109, v3, v25
	v_min_u32_e32 v25, v3, v25
	v_max_u32_e32 v110, v11, v18
	v_min_u32_e32 v18, v11, v18
	v_max_u32_e32 v111, v7, v29
	v_min_u32_e32 v29, v7, v29
	v_max_u32_e32 v1, v10, v22
	v_min_u32_e32 v22, v10, v22
	v_max_u32_e32 v17, v8, v21
	v_min_u32_e32 v21, v8, v21
	v_max_u32_e32 v33, v15, v105
	v_min_u32_e32 v105, v15, v105
	v_max_u32_e32 v49, v14, v28
	v_min_u32_e32 v28, v14, v28
	v_max_u32_e32 v5, v106, v63
	v_max_u32_e32 v24, v38, v58
	v_max_u32_e32 v0, v34, v59
	v_max_u32_e32 v20, v46, v60
	v_max_u32_e32 v104, v37, v56
	v_max_u32_e32 v31, v32, v52
	v_max_u32_e32 v6, v41, v51
	v_max_u32_e32 v26, v39, v61
	v_max_u32_e32 v13, v45, v55
	v_max_u32_e32 v23, v35, v57
	v_max_u32_e32 v9, v36, v48
	v_max_u32_e32 v19, v40, v53
	v_max_u32_e32 v4, v44, v62
	v_max_u32_e32 v16, v43, v50
	v_max_u32_e32 v2, v42, v54
	v_max_u32_e32 v27, v47, v107
	v_max_u32_e32 v12, v5, v13
	v_min_u32_e32 v13, v5, v13
	v_max_u32_e32 v3, v24, v23
	v_min_u32_e32 v23, v24, v23
	v_max_u32_e32 v11, v0, v9
	v_min_u32_e32 v9, v0, v9
	v_max_u32_e32 v7, v20, v19
	v_min_u32_e32 v19, v20, v19
	v_max_u32_e32 v10, v104, v4
	v_min_u32_e32 v4, v104, v4
	v_max_u32_e32 v8, v31, v16
	v_min_u32_e32 v16, v31, v16
	v_max_u32_e32 v15, v6, v2
	v_min_u32_e32 v2, v6, v2
	v_max_u32_e32 v14, v26, v27
	v_min_u32_e32 v27, v26, v27
	v_max_u32_e32 v106, v12, v10
	v_min_u32_e32 v10, v12, v10
	v_max_u32_e32 v63, v3, v8
	v_min_u32_e32 v8, v3, v8
	v_max_u32_e32 v38, v11, v15
	v_min_u32_e32 v15, v11, v15
	v_max_u32_e32 v58, v7, v14
	v_min_u32_e32 v14, v7, v14
	v_max_u32_e32 v34, v13, v4
	v_min_u32_e32 v4, v13, v4
	v_max_u32_e32 v59, v23, v16
	v_min_u32_e32 v16, v23, v16
	v_max_u32_e32 v46, v9, v2
	v_min_u32_e32 v2, v9, v2
	v_max_u32_e32 v60, v19, v27
	v_min_u32_e32 v27, v19, v27
	v_max_u32_e32 v37, v106, v38
	v_min_u32_e32 v38, v106, v38
	v_max_u32_e32 v56, v63, v58
	v_min_u32_e32 v58, v63, v58
	v_max_u32_e32 v32, v10, v15
	v_min_u32_e32 v15, v10, v15
	v_max_u32_e32 v52, v8, v14
	v_min_u32_e32 v14, v8, v14
	v_max_u32_e32 v41, v34, v46
	v_min_u32_e32 v46, v34, v46
	v_max_u32_e32 v51, v59, v60
	v_min_u32_e32 v60, v59, v60
	v_max_u32_e32 v39, v4, v2
	v_min_u32_e32 v2, v4, v2
	v_max_u32_e32 v61, v16, v27
	v_min_u32_e32 v27, v16, v27
	v_max_u32_e32 v45, v37, v56
	v_min_u32_e32 v56, v37, v56
	v_max_u32_e32 v55, v38, v58
	v_min_u32_e32 v58, v38, v58
	v_max_u32_e32 v35, v32, v52
	v_min_u32_e32 v52, v32, v52
	v_max_u32_e32 v57, v15, v14
	v_min_u32_e32 v14, v15, v14
	v_max_u32_e32 v36, v41, v51
	v_min_u32_e32 v51, v41, v51
	v_max_u32_e32 v48, v46, v60
	v_min_u32_e32 v60, v46, v60
	v_max_u32_e32 v40, v39, v61
	v_min_u32_e32 v61, v39, v61
	v_max_u32_e32 v53, v2, v27
	v_min_u32_e32 v27, v2, v27
	v_max_u32_e32 v44, v108, v27
	v_max_u32_e32 v62, v30, v53
	v_max_u32_e32 v43, v109, v61
	v_max_u32_e32 v50, v25, v40
	v_max_u32_e32 v42, v110, v60
	v_max_u32_e32 v54, v18, v48
	v_max_u32_e32 v47, v111, v51
	v_max_u32_e32 v107, v29, v36
	v_max_u32_e32 v5, v1, v14
	v_max_u32_e32 v24, v22, v57
	v_max_u32_e32 v0, v17, v52
	v_max_u32_e32 v20, v21, v35
	v_max_u32_e32 v104, v33, v58
	v_max_u32_e32 v31, v105, v55
	v_max_u32_e32 v6, v49, v56
	v_max_u32_e32 v26, v28, v45
	v_max_u32_e32 v12, v44, v5
	v_min_u32_e32 v5, v44, v5
	v_max_u32_e32 v3, v62, v24
	v_min_u32_e32 v24, v62, v24
	v_max_u32_e32 v11, v43, v0
	v_min_u32_e32 v0, v43, v0
	v_max_u32_e32 v7, v50, v20
	v_min_u32_e32 v20, v50, v20
	v_max_u32_e32 v13, v42, v104
	v_min_u32_e32 v104, v42, v104
	v_max_u32_e32 v23, v54, v31
	v_min_u32_e32 v31, v54, v31
	v_max_u32_e32 v9, v47, v6
	v_min_u32_e32 v6, v47, v6
	v_max_u32_e32 v19, v107, v26
	v_min_u32_e32 v26, v107, v26
	v_max_u32_e32 v106, v12, v13
	v_min_u32_e32 v13, v12, v13
	v_max_u32_e32 v63, v3, v23
	v_min_u32_e32 v23, v3, v23
	v_max_u32_e32 v10, v11, v9
	v_min_u32_e32 v9, v11, v9
	v_max_u32_e32 v8, v7, v19
	v_min_u32_e32 v19, v7, v19
	v_max_u32_e32 v34, v5, v104
	v_min_u32_e32 v104, v5, v104
	v_max_u32_e32 v59, v24, v31
	v_min_u32_e32 v31, v24, v31
	v_max_u32_e32 v4, v0, v6
	v_min_u32_e32 v6, v0, v6
	v_max_u32_e32 v16, v20, v26
	v_min_u32_e32 v26, v20, v26
	v_max_u32_e32 v37, v106, v10
	v_min_u32_e32 v10, v106, v10
	v_max_u32_e32 v38, v63, v8
	v_min_u32_e32 v8, v63, v8
	v_max_u32_e32 v32, v13, v9
	v_min_u32_e32 v9, v13, v9
	v_max_u32_e32 v15, v23, v19
	v_min_u32_e32 v19, v23, v19
	v_max_u32_e32 v41, v34, v4
	v_min_u32_e32 v4, v34, v4
	v_max_u32_e32 v46, v59, v16
	v_min_u32_e32 v16, v59, v16
	v_max_u32_e32 v39, v104, v6
	v_min_u32_e32 v6, v104, v6
	v_max_u32_e32 v2, v31, v26
	v_min_u32_e32 v26, v31, v26
	v_max_u32_e32 v108, v37, v38
	v_min_u32_e32 v38, v37, v38
	v_max_u32_e32 v27, v10, v8
	v_min_u32_e32 v8, v10, v8
	v_max_u32_e32 v30, v32, v15
	v_min_u32_e32 v15, v32, v15
	v_max_u32_e32 v53, v9, v19
	v_min_u32_e32 v19, v9, v19
	v_max_u32_e32 v109, v41, v46
	v_min_u32_e32 v46, v41, v46
	v_max_u32_e32 v61, v4, v16
	v_min_u32_e32 v16, v4, v16
	v_max_u32_e32 v25, v39, v2
	v_min_u32_e32 v2, v39, v2
	v_max_u32_e32 v40, v6, v26
	v_min_u32_e32 v26, v6, v26
	s_nop 1
	v_max_u32_dpp v110, v26, v108 quad_perm:[1,0,3,2] row_mask:0xf bank_mask:0xf
	v_max_u32_dpp v60, v40, v38 quad_perm:[1,0,3,2] row_mask:0xf bank_mask:0xf
	v_max_u32_dpp v18, v2, v27 quad_perm:[1,0,3,2] row_mask:0xf bank_mask:0xf
	v_max_u32_dpp v48, v25, v8 quad_perm:[1,0,3,2] row_mask:0xf bank_mask:0xf
	v_max_u32_dpp v111, v16, v30 quad_perm:[1,0,3,2] row_mask:0xf bank_mask:0xf
	v_max_u32_dpp v51, v61, v15 quad_perm:[1,0,3,2] row_mask:0xf bank_mask:0xf
	v_max_u32_dpp v29, v46, v53 quad_perm:[1,0,3,2] row_mask:0xf bank_mask:0xf
	v_max_u32_dpp v36, v109, v19 quad_perm:[1,0,3,2] row_mask:0xf bank_mask:0xf
	v_max_u32_dpp v1, v19, v109 quad_perm:[1,0,3,2] row_mask:0xf bank_mask:0xf
	v_max_u32_dpp v14, v53, v46 quad_perm:[1,0,3,2] row_mask:0xf bank_mask:0xf
	v_max_u32_dpp v22, v15, v61 quad_perm:[1,0,3,2] row_mask:0xf bank_mask:0xf
	v_max_u32_dpp v57, v30, v16 quad_perm:[1,0,3,2] row_mask:0xf bank_mask:0xf
	v_max_u32_dpp v17, v8, v25 quad_perm:[1,0,3,2] row_mask:0xf bank_mask:0xf
	v_max_u32_dpp v52, v27, v2 quad_perm:[1,0,3,2] row_mask:0xf bank_mask:0xf
	v_max_u32_dpp v21, v38, v40 quad_perm:[1,0,3,2] row_mask:0xf bank_mask:0xf
	v_max_u32_dpp v35, v108, v26 quad_perm:[1,0,3,2] row_mask:0xf bank_mask:0xf
	v_max_u32_e32 v33, v110, v1
	v_min_u32_e32 v1, v110, v1
	v_max_u32_e32 v58, v60, v14
	v_min_u32_e32 v14, v60, v14
	v_max_u32_e32 v105, v18, v22
	v_min_u32_e32 v22, v18, v22
	v_max_u32_e32 v55, v48, v57
	v_min_u32_e32 v57, v48, v57
	v_max_u32_e32 v49, v111, v17
	v_min_u32_e32 v17, v111, v17
	v_max_u32_e32 v56, v51, v52
	v_min_u32_e32 v52, v51, v52
	v_max_u32_e32 v28, v29, v21
	v_min_u32_e32 v21, v29, v21
	v_max_u32_e32 v45, v36, v35
	v_min_u32_e32 v35, v36, v35
	v_max_u32_e32 v44, v33, v49
	v_min_u32_e32 v49, v33, v49
	v_max_u32_e32 v62, v58, v56
	v_min_u32_e32 v56, v58, v56
	v_max_u32_e32 v43, v105, v28
	v_min_u32_e32 v28, v105, v28
	v_max_u32_e32 v50, v55, v45
	v_min_u32_e32 v45, v55, v45
	v_max_u32_e32 v42, v1, v17
	v_min_u32_e32 v17, v1, v17
	v_max_u32_e32 v54, v14, v52
	v_min_u32_e32 v52, v14, v52
	v_max_u32_e32 v47, v22, v21
	v_min_u32_e32 v21, v22, v21
	v_max_u32_e32 v107, v57, v35
	v_min_u32_e32 v35, v57, v35
	v_max_u32_e32 v12, v44, v43
	v_min_u32_e32 v43, v44, v43
	v_max_u32_e32 v3, v62, v50
	v_min_u32_e32 v50, v62, v50
	v_max_u32_e32 v11, v49, v28
	v_min_u32_e32 v28, v49, v28
	v_max_u32_e32 v7, v56, v45
	v_min_u32_e32 v45, v56, v45
	v_max_u32_e32 v5, v42, v47
	v_min_u32_e32 v47, v42, v47
	v_max_u32_e32 v24, v54, v107
	v_min_u32_e32 v107, v54, v107
	v_max_u32_e32 v0, v17, v21
	v_min_u32_e32 v21, v17, v21
	v_max_u32_e32 v20, v52, v35
	v_min_u32_e32 v35, v52, v35
	v_max_u32_e32 v106, v12, v3
	v_min_u32_e32 v3, v12, v3
	v_max_u32_e32 v63, v43, v50
	v_min_u32_e32 v50, v43, v50
	v_max_u32_e32 v13, v11, v7
	v_min_u32_e32 v7, v11, v7
	v_max_u32_e32 v23, v28, v45
	v_min_u32_e32 v45, v28, v45
	v_max_u32_e32 v34, v5, v24
	v_min_u32_e32 v24, v5, v24
	v_max_u32_e32 v59, v47, v107
	v_min_u32_e32 v107, v47, v107
	v_max_u32_e32 v104, v0, v20
	v_min_u32_e32 v20, v0, v20
	v_max_u32_e32 v31, v21, v35
	v_min_u32_e32 v35, v21, v35
	v_cmp_eq_u32_e32 vcc, 1, v117
	v_lshl_add_u32 v119, s16, 7, v116
	v_lshlrev_b32_e32 v119, 10, v119
	s_lshl_b32 s20, s20, 6
	v_lshl_add_u32 v119, v117, 5, v119
	v_add_u32_e32 v119, s20, v119
	v_cndmask_b32_e32 v120, v106, v34, vcc
	v_cndmask_b32_e32 v121, v3, v24, vcc
	v_cndmask_b32_e32 v122, v63, v59, vcc
	v_cndmask_b32_e32 v123, v50, v107, vcc
	v_cndmask_b32_e32 v124, v13, v104, vcc
	v_cndmask_b32_e32 v125, v7, v20, vcc
	v_cndmask_b32_e32 v126, v23, v31, vcc
	v_cndmask_b32_e32 v127, v45, v35, vcc
	v_xor_b32_e32 v120, 0x7f, v120
	v_xor_b32_e32 v121, 0x7f, v121
	v_xor_b32_e32 v122, 0x7f, v122
	v_xor_b32_e32 v123, 0x7f, v123
	v_xor_b32_e32 v124, 0x7f, v124
	v_xor_b32_e32 v125, 0x7f, v125
	v_xor_b32_e32 v126, 0x7f, v126
	v_xor_b32_e32 v127, 0x7f, v127
	global_store_dwordx4 v119, v[120:123], s[22:23]
	global_store_dwordx4 v119, v[124:127], s[22:23] offset:16
	s_branch .LBB0_19
